# saddr+peel plus leading-half ALIGN_EPI barrier moved down to the epilogue's first vmcnt(0) (row-stat/residual loads issued before the barrier)
# baseline (speedup 1.0000x reference)
; __device__ __forceinline__ void rows_rstd(const float* ssq, int row0, int fq, float (&rs)[2][4]) {
;     f32x4 p[2][4];
; #pragma unroll
;     for (int ai = 0; ai < 2; ++ai)
; #pragma unroll
;         for (int m = 0; m < 4; ++m) p[ai][m] = *(const f32x4*)(ssq + (size_t)(row0 + ai * HALF + m * 16) * 16 + 4 * fq);
; #pragma unroll
;     for (int ai = 0; ai < 2; ++ai)
; #pragma unroll
;         for (int m = 0; m < 4; ++m) { float s = (p[ai][m][0] + p[ai][m][1]) + (p[ai][m][2] + p[ai][m][3]); s += __shfl_xor(s, 16); s += __shfl_xor(s, 32); rs[ai][m] = __builtin_amdgcn_rsqf(s * (1.0f / (float)DM) + RMS_EPS); }
; }
;     __device__ __forceinline__ void operator()(const f32x4 (&acc)[2][2][4][2], const Unit& u, int wr, int wc, int fr, int fq) const {
;         const int row0 = u.pm * BM + wr * 64 + fr, col0 = u.pn * HALF + wc * 32 + 8 * fq;
;         float rsv[2][4]; rows_rstd(ssq, row0, fq, rsv);
; #pragma unroll
;         for (int ai = 0; ai < 2; ++ai)
; #pragma unroll
;             for (int m = 0; m < 4; ++m) {
;                 const int row = row0 + ai * HALF + m * 16; const float rs = rsv[ai][m], cexp = -1.4426950408889634f * rs, rs2 = rs * rs;
;                 const f32x4 g0 = acc[ai][0][m][0], g1 = acc[ai][0][m][1], u0 = acc[ai][1][m][0], u1 = acc[ai][1][m][1];
;                 const f32x4 t0 = g0 * cexp, t1 = g1 * cexp;
;                 f32x4 d0 = (f32x4){__builtin_amdgcn_exp2f(t0[0]), __builtin_amdgcn_exp2f(t0[1]), __builtin_amdgcn_exp2f(t0[2]), __builtin_amdgcn_exp2f(t0[3])} + 1.0f;
;                 f32x4 d1 = (f32x4){__builtin_amdgcn_exp2f(t1[0]), __builtin_amdgcn_exp2f(t1[1]), __builtin_amdgcn_exp2f(t1[2]), __builtin_amdgcn_exp2f(t1[3])} + 1.0f;
;                 const f32x4 r0 = (f32x4){__builtin_amdgcn_rcpf(d0[0]), __builtin_amdgcn_rcpf(d0[1]), __builtin_amdgcn_rcpf(d0[2]), __builtin_amdgcn_rcpf(d0[3])} * rs2;
;                 const f32x4 r1 = (f32x4){__builtin_amdgcn_rcpf(d1[0]), __builtin_amdgcn_rcpf(d1[1]), __builtin_amdgcn_rcpf(d1[2]), __builtin_amdgcn_rcpf(d1[3])} * rs2;
;                 const f32x4 a0 = (g0 * u0) * r0, a1 = (g1 * u1) * r1;
;                 u32x4 w; w.x = cvt_pk_bf16(a0[0], a0[1]); w.y = cvt_pk_bf16(a0[2], a0[3]); w.z = cvt_pk_bf16(a1[0], a1[1]); w.w = cvt_pk_bf16(a1[2], a1[3]);
;                 *(u32x4*)(O + (((size_t)(row >> 8) * (DFF / BK) + (col0 >> 6)) * BM + (row & 255)) * BK + (col0 & 63)) = w;
.LBB0_136:
	s_lshl_b32 s43, s48, 8
	s_add_i32 s43, s43, s74
	v_or_b32_e32 v152, s43, v154
	v_ashrrev_i32_e32 v153, 31, v152
	v_lshlrev_b64 v[150:151], 6, v[152:153]
	v_lshl_add_u64 v[182:183], v[138:139], 0, v[150:151]
	v_or_b32_e32 v150, 16, v152
	v_ashrrev_i32_e32 v151, 31, v150
	v_lshlrev_b64 v[150:151], 6, v[150:151]
	v_lshl_add_u64 v[150:151], v[138:139], 0, v[150:151]
	global_load_dwordx4 v[162:165], v[182:183], off
	global_load_dwordx4 v[166:169], v[150:151], off
	v_or_b32_e32 v150, 32, v152
	v_or_b32_e32 v170, 48, v152
	v_ashrrev_i32_e32 v151, 31, v150
	v_ashrrev_i32_e32 v171, 31, v170
	v_lshlrev_b64 v[150:151], 6, v[150:151]
	v_lshlrev_b64 v[170:171], 6, v[170:171]
	v_lshl_add_u64 v[150:151], v[138:139], 0, v[150:151]
	v_lshl_add_u64 v[174:175], v[138:139], 0, v[170:171]
	global_load_dwordx4 v[170:173], v[150:151], off
	s_nop 0
	global_load_dwordx4 v[174:177], v[174:175], off
	v_add_u32_e32 v150, 0x80, v152
	v_ashrrev_i32_e32 v151, 31, v150
	v_lshlrev_b64 v[178:179], 6, v[150:151]
	v_lshl_add_u64 v[178:179], v[138:139], 0, v[178:179]
	global_load_dwordx4 v[178:181], v[178:179], off
	v_add_co_u32_e32 v190, vcc, s71, v182
	v_and_b32_e32 v149, 64, v159
	s_nop 0
	v_addc_co_u32_e32 v191, vcc, 0, v183, vcc
	global_load_dwordx4 v[182:185], v[190:191], off offset:1024
	global_load_dwordx4 v[186:189], v[190:191], off offset:2048
	v_xor_b32_e32 v136, 16, v159
	global_load_dwordx4 v[190:193], v[190:191], off offset:3072
	v_add_u32_e32 v149, 64, v149
	v_xor_b32_e32 v151, 32, v159
	v_cmp_lt_i32_e32 vcc, v136, v149
	s_lshl_b32 s41, s81, 7
	s_or_b32 s41, s41, s75
	v_cndmask_b32_e32 v136, v159, v136, vcc
	v_cmp_lt_i32_e32 vcc, v151, v149
	v_lshlrev_b32_e32 v136, 2, v136
	s_ashr_i32 s43, s43, 8
	v_cndmask_b32_e32 v149, v159, v151, vcc
	v_lshlrev_b32_e32 v149, 2, v149
	s_ashr_i32 s41, s41, 6
	s_mul_i32 s43, s43, 44
	s_add_i32 s60, s43, s41
	s_ashr_i32 s61, s60, 31
	v_pk_mul_f32 v[116:117], v[124:125], v[116:117]
	s_lshl_b64 s[60:61], s[60:61], 15
	v_pk_mul_f32 v[114:115], v[122:123], v[114:115]
	v_pk_mul_f32 v[112:113], v[120:121], v[112:113]
	s_add_u32 s60, s36, s60
	v_pk_mul_f32 v[118:119], v[126:127], v[118:119]
	s_addc_u32 s61, s37, s61
	v_pk_mul_f32 v[102:103], v[110:111], v[102:103]
	v_pk_mul_f32 v[100:101], v[108:109], v[100:101]
	v_pk_mul_f32 v[98:99], v[106:107], v[98:99]
	v_pk_mul_f32 v[96:97], v[104:105], v[96:97]
	v_pk_mul_f32 v[84:85], v[92:93], v[84:85]
	v_pk_mul_f32 v[86:87], v[94:95], v[86:87]
	v_pk_mul_f32 v[82:83], v[90:91], v[82:83]
	v_pk_mul_f32 v[80:81], v[88:89], v[80:81]
	v_pk_mul_f32 v[70:71], v[78:79], v[70:71]
	v_pk_mul_f32 v[68:69], v[76:77], v[68:69]
	v_pk_mul_f32 v[66:67], v[74:75], v[66:67]
	v_pk_mul_f32 v[64:65], v[72:73], v[64:65]
	v_pk_mul_f32 v[54:55], v[62:63], v[54:55]
	v_pk_mul_f32 v[52:53], v[60:61], v[52:53]
	v_pk_mul_f32 v[50:51], v[58:59], v[50:51]
	v_pk_mul_f32 v[48:49], v[56:57], v[48:49]
	v_pk_mul_f32 v[38:39], v[46:47], v[38:39]
	v_pk_mul_f32 v[36:37], v[44:45], v[36:37]
	v_pk_mul_f32 v[34:35], v[42:43], v[34:35]
	v_pk_mul_f32 v[32:33], v[40:41], v[32:33]
	v_pk_mul_f32 v[20:21], v[28:29], v[20:21]
	v_pk_mul_f32 v[22:23], v[30:31], v[22:23]
	v_pk_mul_f32 v[18:19], v[26:27], v[18:19]
	v_pk_mul_f32 v[16:17], v[24:25], v[16:17]
	v_pk_mul_f32 v[6:7], v[14:15], v[6:7]
	v_pk_mul_f32 v[4:5], v[12:13], v[4:5]
	v_pk_mul_f32 v[2:3], v[10:11], v[2:3]
	v_pk_mul_f32 v[0:1], v[8:9], v[0:1]
	s_cmp_lg_u64 s[38:39], 0
	s_cbranch_scc0 .Lalign2_skip0
	s_barrier
.Lalign2_skip0:
	s_waitcnt vmcnt(0)
	v_mov_b32_e32 v194, v163
	v_mov_b32_e32 v195, v164
	v_mov_b32_e32 v163, v165
	v_pk_add_f32 v[162:163], v[194:195], v[162:163]
	v_mov_b32_e32 v164, v167
	v_mov_b32_e32 v165, v168
	v_mov_b32_e32 v167, v169
	v_add_f32_e32 v151, v162, v163
	v_pk_add_f32 v[162:163], v[164:165], v[166:167]
	v_mov_b32_e32 v168, v171
	v_mov_b32_e32 v169, v172
	v_mov_b32_e32 v171, v173
	v_mov_b32_e32 v172, v175
	v_mov_b32_e32 v173, v176
	v_mov_b32_e32 v175, v177
	v_mov_b32_e32 v176, v179
	v_mov_b32_e32 v177, v180
	v_mov_b32_e32 v179, v181
	v_pk_add_f32 v[164:165], v[168:169], v[170:171]
	v_pk_add_f32 v[166:167], v[172:173], v[174:175]
	ds_bpermute_b32 v153, v136, v151
	v_add_f32_e32 v161, v162, v163
	v_pk_add_f32 v[168:169], v[176:177], v[178:179]
	v_add_f32_e32 v162, v164, v165
	v_add_f32_e32 v163, v166, v167
	ds_bpermute_b32 v166, v136, v161
	v_add_f32_e32 v164, v168, v169
	ds_bpermute_b32 v167, v136, v162
	ds_bpermute_b32 v168, v136, v163
	ds_bpermute_b32 v169, v136, v164
	s_waitcnt lgkmcnt(4)
	v_add_f32_e32 v151, v151, v153
	ds_bpermute_b32 v153, v149, v151
	s_waitcnt lgkmcnt(4)
	v_add_f32_e32 v161, v161, v166
	s_waitcnt lgkmcnt(3)
	v_add_f32_e32 v162, v162, v167
	s_waitcnt lgkmcnt(2)
	v_add_f32_e32 v163, v163, v168
	ds_bpermute_b32 v166, v149, v161
	v_mov_b32_e32 v180, v183
	v_mov_b32_e32 v181, v184
	v_mov_b32_e32 v183, v185
	s_waitcnt lgkmcnt(2)
	v_add_f32_e32 v164, v164, v169
	ds_bpermute_b32 v167, v149, v162
	ds_bpermute_b32 v168, v149, v163
	v_pk_add_f32 v[170:171], v[180:181], v[182:183]
	ds_bpermute_b32 v169, v149, v164
	v_add_f32_e32 v165, v170, v171
	ds_bpermute_b32 v170, v136, v165
	s_waitcnt lgkmcnt(5)
	v_add_f32_e32 v151, v151, v153
	v_fmamk_f32 v151, v151, 0x3a800000, v160
	s_waitcnt lgkmcnt(4)
	v_add_f32_e32 v153, v161, v166
	s_waitcnt lgkmcnt(3)
	v_add_f32_e32 v161, v162, v167
	s_waitcnt lgkmcnt(2)
	v_add_f32_e32 v162, v163, v168
	v_rsq_f32_e32 v166, v151
	v_fmamk_f32 v151, v153, 0x3a800000, v160
	v_fmamk_f32 v153, v161, 0x3a800000, v160
	v_fmamk_f32 v161, v162, 0x3a800000, v160
	v_rsq_f32_e32 v172, v151
	s_waitcnt lgkmcnt(1)
; __device__ __forceinline__ unsigned cvt_pk_bf16(float lo, float hi) { typedef float f2 __attribute__((ext_vector_type(2))); const bf16v2 r = __builtin_convertvector((f2){lo, hi}, bf16v2); return __builtin_bit_cast(unsigned, r); }
;     __device__ __forceinline__ void operator()(const f32x4 (&acc)[2][2][4][2], const Unit& u, int wr, int wc, int fr, int fq) const {
;     ...
;         for (int ai = 0; ai < 2; ++ai)
; #pragma unroll
;             for (int m = 0; m < 4; ++m) {
;                 const int row = row0 + ai * HALF + m * 16; const float rs = rsv[ai][m], cexp = -1.4426950408889634f * rs, rs2 = rs * rs;
;                 const f32x4 g0 = acc[ai][0][m][0], g1 = acc[ai][0][m][1], u0 = acc[ai][1][m][0], u1 = acc[ai][1][m][1];
;                 const f32x4 t0 = g0 * cexp, t1 = g1 * cexp;
;                 f32x4 d0 = (f32x4){__builtin_amdgcn_exp2f(t0[0]), __builtin_amdgcn_exp2f(t0[1]), __builtin_amdgcn_exp2f(t0[2]), __builtin_amdgcn_exp2f(t0[3])} + 1.0f;
;                 f32x4 d1 = (f32x4){__builtin_amdgcn_exp2f(t1[0]), __builtin_amdgcn_exp2f(t1[1]), __builtin_amdgcn_exp2f(t1[2]), __builtin_amdgcn_exp2f(t1[3])} + 1.0f;
;                 const f32x4 r0 = (f32x4){__builtin_amdgcn_rcpf(d0[0]), __builtin_amdgcn_rcpf(d0[1]), __builtin_amdgcn_rcpf(d0[2]), __builtin_amdgcn_rcpf(d0[3])} * rs2;
;                 const f32x4 r1 = (f32x4){__builtin_amdgcn_rcpf(d1[0]), __builtin_amdgcn_rcpf(d1[1]), __builtin_amdgcn_rcpf(d1[2]), __builtin_amdgcn_rcpf(d1[3])} * rs2;
;                 const f32x4 a0 = (g0 * u0) * r0, a1 = (g1 * u1) * r1;
;                 u32x4 w; w.x = cvt_pk_bf16(a0[0], a0[1]); w.y = cvt_pk_bf16(a0[2], a0[3]); w.z = cvt_pk_bf16(a1[0], a1[1]); w.w = cvt_pk_bf16(a1[2], a1[3]);
;                 *(u32x4*)(O + (((size_t)(row >> 8) * (DFF / BK) + (col0 >> 6)) * BM + (row & 255)) * BK + (col0 & 63)) = w;
	v_add_f32_e32 v151, v164, v169
	v_mov_b32_e32 v162, v187
	v_mov_b32_e32 v163, v188
	v_mov_b32_e32 v187, v189
	v_fmamk_f32 v151, v151, 0x3a800000, v160
	v_pk_add_f32 v[162:163], v[162:163], v[186:187]
	v_rsq_f32_e32 v173, v151
	s_waitcnt lgkmcnt(0)
	v_add_f32_e32 v151, v165, v170
	v_add_f32_e32 v165, v162, v163
	v_mov_b32_e32 v162, v191
	v_mov_b32_e32 v163, v192
	v_mov_b32_e32 v191, v193
	v_pk_add_f32 v[162:163], v[162:163], v[190:191]
	ds_bpermute_b32 v167, v136, v165
	v_add_f32_e32 v162, v162, v163
	ds_bpermute_b32 v136, v136, v162
	ds_bpermute_b32 v164, v149, v151
	v_rsq_f32_e32 v153, v153
	s_waitcnt lgkmcnt(2)
	v_add_f32_e32 v163, v165, v167
	v_rsq_f32_e32 v161, v161
	s_waitcnt lgkmcnt(1)
	v_add_f32_e32 v136, v162, v136
	s_waitcnt lgkmcnt(0)
	v_add_f32_e32 v151, v151, v164
	ds_bpermute_b32 v164, v149, v163
	ds_bpermute_b32 v149, v149, v136
	v_fmamk_f32 v151, v151, 0x3a800000, v160
	v_rsq_f32_e32 v174, v151
	v_mul_f32_e32 v162, v166, v166
	s_waitcnt lgkmcnt(1)
	v_add_f32_e32 v151, v163, v164
	s_waitcnt lgkmcnt(0)
	v_add_f32_e32 v136, v136, v149
	v_fmamk_f32 v151, v151, 0x3a800000, v160
	v_fmamk_f32 v136, v136, 0x3a800000, v160
	v_rsq_f32_e32 v175, v151
	v_rsq_f32_e32 v151, v136
	v_mul_f32_e32 v136, 0xbfb8aa3b, v166
	v_pk_mul_f32 v[166:167], v[124:125], v[136:137] op_sel_hi:[1,0]
	v_pk_mul_f32 v[164:165], v[126:127], v[136:137] op_sel_hi:[1,0]
	v_pk_mul_f32 v[168:169], v[122:123], v[136:137] op_sel_hi:[1,0]
	v_pk_mul_f32 v[170:171], v[120:121], v[136:137] op_sel_hi:[1,0]
	v_exp_f32_e32 v166, v166
	v_exp_f32_e32 v167, v167
	v_exp_f32_e32 v164, v164
	v_exp_f32_e32 v165, v165
	v_exp_f32_e32 v170, v170
	v_exp_f32_e32 v168, v168
	v_exp_f32_e32 v169, v169
	v_exp_f32_e32 v171, v171
	v_pk_add_f32 v[166:167], v[166:167], 1.0 op_sel_hi:[1,0]
	v_pk_add_f32 v[164:165], v[164:165], 1.0 op_sel_hi:[1,0]
	v_pk_add_f32 v[168:169], v[168:169], 1.0 op_sel_hi:[1,0]
	v_pk_add_f32 v[170:171], v[170:171], 1.0 op_sel_hi:[1,0]
	v_rcp_f32_e32 v166, v166
	v_rcp_f32_e32 v167, v167
	v_rcp_f32_e32 v164, v164
	v_rcp_f32_e32 v165, v165
	v_rcp_f32_e32 v170, v170
	v_rcp_f32_e32 v171, v171
	v_rcp_f32_e32 v168, v168
	v_rcp_f32_e32 v169, v169
	v_pk_mul_f32 v[166:167], v[162:163], v[166:167] op_sel_hi:[0,1]
	v_pk_mul_f32 v[164:165], v[162:163], v[164:165] op_sel_hi:[0,1]
	v_pk_mul_f32 v[170:171], v[162:163], v[170:171] op_sel_hi:[0,1]
	v_pk_mul_f32 v[162:163], v[162:163], v[168:169] op_sel_hi:[0,1]
	v_pk_mul_f32 v[116:117], v[116:117], v[166:167]
	v_pk_mul_f32 v[120:121], v[114:115], v[162:163]
	v_pk_mul_f32 v[114:115], v[112:113], v[170:171]
	v_cvt_pk_bf16_f32 v112, v116, v117
	v_lshlrev_b32_e32 v116, 7, v152
	v_and_b32_e32 v136, 0x6780, v116
	v_pk_mul_f32 v[118:119], v[118:119], v[164:165]
	v_lshl_add_u64 v[116:117], s[60:61], 0, v[136:137]
	v_mov_b32_e32 v149, v137
	v_cvt_pk_bf16_f32 v113, v118, v119
	v_cvt_pk_bf16_f32 v114, v114, v115
	v_cvt_pk_bf16_f32 v115, v120, v121
	v_lshl_add_u64 v[116:117], v[116:117], 0, v[148:149]
	global_store_dwordx4 v[116:117], v[112:115], off
	s_nop 1
	v_mul_f32_e32 v112, 0xbfb8aa3b, v172
	v_pk_mul_f32 v[118:119], v[110:111], v[112:113] op_sel_hi:[1,0]
	v_pk_mul_f32 v[120:121], v[108:109], v[112:113] op_sel_hi:[1,0]
	v_pk_mul_f32 v[122:123], v[106:107], v[112:113] op_sel_hi:[1,0]
	v_pk_mul_f32 v[112:113], v[104:105], v[112:113] op_sel_hi:[1,0]
	v_exp_f32_e32 v120, v120
	v_exp_f32_e32 v121, v121
	v_exp_f32_e32 v118, v118
	v_exp_f32_e32 v119, v119
	v_exp_f32_e32 v112, v112
	v_exp_f32_e32 v122, v122
	v_exp_f32_e32 v123, v123
	v_exp_f32_e32 v113, v113
	v_pk_add_f32 v[118:119], v[118:119], 1.0 op_sel_hi:[1,0]
	v_pk_add_f32 v[120:121], v[120:121], 1.0 op_sel_hi:[1,0]
	v_pk_add_f32 v[122:123], v[122:123], 1.0 op_sel_hi:[1,0]
	v_pk_add_f32 v[112:113], v[112:113], 1.0 op_sel_hi:[1,0]
	v_rcp_f32_e32 v120, v120
	v_rcp_f32_e32 v121, v121
	v_rcp_f32_e32 v118, v118
	v_rcp_f32_e32 v119, v119
	v_rcp_f32_e32 v112, v112
	v_rcp_f32_e32 v113, v113
	v_rcp_f32_e32 v122, v122
	v_rcp_f32_e32 v123, v123
	v_mul_f32_e32 v114, v172, v172
	v_pk_mul_f32 v[120:121], v[114:115], v[120:121] op_sel_hi:[0,1]
	v_pk_mul_f32 v[118:119], v[114:115], v[118:119] op_sel_hi:[0,1]
	v_pk_mul_f32 v[112:113], v[114:115], v[112:113] op_sel_hi:[0,1]
	v_pk_mul_f32 v[114:115], v[114:115], v[122:123] op_sel_hi:[0,1]
	v_pk_mul_f32 v[102:103], v[102:103], v[118:119]
	v_pk_mul_f32 v[100:101], v[100:101], v[120:121]
	v_pk_mul_f32 v[104:105], v[98:99], v[114:115]
	v_pk_mul_f32 v[98:99], v[96:97], v[112:113]
	v_cvt_pk_bf16_f32 v96, v100, v101
	v_cvt_pk_bf16_f32 v97, v102, v103
	v_cvt_pk_bf16_f32 v98, v98, v99
	v_cvt_pk_bf16_f32 v99, v104, v105
	global_store_dwordx4 v[116:117], v[96:99], off offset:2048
	s_nop 1
	v_mul_f32_e32 v96, 0xbfb8aa3b, v153
	v_pk_mul_f32 v[102:103], v[92:93], v[96:97] op_sel_hi:[1,0]
	v_pk_mul_f32 v[100:101], v[94:95], v[96:97] op_sel_hi:[1,0]
	v_pk_mul_f32 v[104:105], v[90:91], v[96:97] op_sel_hi:[1,0]
	v_pk_mul_f32 v[96:97], v[88:89], v[96:97] op_sel_hi:[1,0]
	v_exp_f32_e32 v102, v102
	v_exp_f32_e32 v103, v103
	v_exp_f32_e32 v100, v100
	v_exp_f32_e32 v101, v101
	v_exp_f32_e32 v96, v96
	v_exp_f32_e32 v104, v104
	v_exp_f32_e32 v105, v105
	v_exp_f32_e32 v97, v97
	v_pk_add_f32 v[102:103], v[102:103], 1.0 op_sel_hi:[1,0]
	v_pk_add_f32 v[100:101], v[100:101], 1.0 op_sel_hi:[1,0]
	v_pk_add_f32 v[104:105], v[104:105], 1.0 op_sel_hi:[1,0]
	v_pk_add_f32 v[96:97], v[96:97], 1.0 op_sel_hi:[1,0]
	v_rcp_f32_e32 v102, v102
	v_rcp_f32_e32 v103, v103
	v_rcp_f32_e32 v100, v100
	v_rcp_f32_e32 v101, v101
	v_rcp_f32_e32 v96, v96
	v_rcp_f32_e32 v97, v97
	v_rcp_f32_e32 v104, v104
	v_rcp_f32_e32 v105, v105
	v_mul_f32_e32 v98, v153, v153
	v_pk_mul_f32 v[102:103], v[98:99], v[102:103] op_sel_hi:[0,1]
; __device__ __forceinline__ unsigned cvt_pk_bf16(float lo, float hi) { typedef float f2 __attribute__((ext_vector_type(2))); const bf16v2 r = __builtin_convertvector((f2){lo, hi}, bf16v2); return __builtin_bit_cast(unsigned, r); }
;     __device__ __forceinline__ void operator()(const f32x4 (&acc)[2][2][4][2], const Unit& u, int wr, int wc, int fr, int fq) const {
;     ...
;         for (int ai = 0; ai < 2; ++ai)
; #pragma unroll
;             for (int m = 0; m < 4; ++m) {
;                 const int row = row0 + ai * HALF + m * 16; const float rs = rsv[ai][m], cexp = -1.4426950408889634f * rs, rs2 = rs * rs;
;                 const f32x4 g0 = acc[ai][0][m][0], g1 = acc[ai][0][m][1], u0 = acc[ai][1][m][0], u1 = acc[ai][1][m][1];
;                 const f32x4 t0 = g0 * cexp, t1 = g1 * cexp;
;                 f32x4 d0 = (f32x4){__builtin_amdgcn_exp2f(t0[0]), __builtin_amdgcn_exp2f(t0[1]), __builtin_amdgcn_exp2f(t0[2]), __builtin_amdgcn_exp2f(t0[3])} + 1.0f;
;                 f32x4 d1 = (f32x4){__builtin_amdgcn_exp2f(t1[0]), __builtin_amdgcn_exp2f(t1[1]), __builtin_amdgcn_exp2f(t1[2]), __builtin_amdgcn_exp2f(t1[3])} + 1.0f;
;                 const f32x4 r0 = (f32x4){__builtin_amdgcn_rcpf(d0[0]), __builtin_amdgcn_rcpf(d0[1]), __builtin_amdgcn_rcpf(d0[2]), __builtin_amdgcn_rcpf(d0[3])} * rs2;
;                 const f32x4 r1 = (f32x4){__builtin_amdgcn_rcpf(d1[0]), __builtin_amdgcn_rcpf(d1[1]), __builtin_amdgcn_rcpf(d1[2]), __builtin_amdgcn_rcpf(d1[3])} * rs2;
;                 const f32x4 a0 = (g0 * u0) * r0, a1 = (g1 * u1) * r1;
;                 u32x4 w; w.x = cvt_pk_bf16(a0[0], a0[1]); w.y = cvt_pk_bf16(a0[2], a0[3]); w.z = cvt_pk_bf16(a1[0], a1[1]); w.w = cvt_pk_bf16(a1[2], a1[3]);
;                 *(u32x4*)(O + (((size_t)(row >> 8) * (DFF / BK) + (col0 >> 6)) * BM + (row & 255)) * BK + (col0 & 63)) = w;
	v_pk_mul_f32 v[100:101], v[98:99], v[100:101] op_sel_hi:[0,1]
	v_pk_mul_f32 v[96:97], v[98:99], v[96:97] op_sel_hi:[0,1]
	v_pk_mul_f32 v[98:99], v[98:99], v[104:105] op_sel_hi:[0,1]
	v_pk_mul_f32 v[84:85], v[84:85], v[102:103]
	v_pk_mul_f32 v[86:87], v[86:87], v[100:101]
	v_pk_mul_f32 v[88:89], v[82:83], v[98:99]
	v_pk_mul_f32 v[82:83], v[80:81], v[96:97]
	v_cvt_pk_bf16_f32 v80, v84, v85
	v_add_co_u32_e32 v84, vcc, s80, v116
	v_cvt_pk_bf16_f32 v81, v86, v87
	v_cvt_pk_bf16_f32 v82, v82, v83
	v_cvt_pk_bf16_f32 v83, v88, v89
	v_addc_co_u32_e32 v85, vcc, 0, v117, vcc
	global_store_dwordx4 v[84:85], v[80:83], off
	s_nop 1
	v_mul_f32_e32 v80, 0xbfb8aa3b, v161
	v_pk_mul_f32 v[86:87], v[78:79], v[80:81] op_sel_hi:[1,0]
	v_pk_mul_f32 v[88:89], v[76:77], v[80:81] op_sel_hi:[1,0]
	v_pk_mul_f32 v[90:91], v[74:75], v[80:81] op_sel_hi:[1,0]
	v_pk_mul_f32 v[80:81], v[72:73], v[80:81] op_sel_hi:[1,0]
	v_exp_f32_e32 v88, v88
	v_exp_f32_e32 v89, v89
	v_exp_f32_e32 v86, v86
	v_exp_f32_e32 v87, v87
	v_exp_f32_e32 v80, v80
	v_exp_f32_e32 v90, v90
	v_exp_f32_e32 v91, v91
	v_exp_f32_e32 v81, v81
	v_pk_add_f32 v[86:87], v[86:87], 1.0 op_sel_hi:[1,0]
	v_pk_add_f32 v[88:89], v[88:89], 1.0 op_sel_hi:[1,0]
	v_pk_add_f32 v[90:91], v[90:91], 1.0 op_sel_hi:[1,0]
	v_pk_add_f32 v[80:81], v[80:81], 1.0 op_sel_hi:[1,0]
	v_rcp_f32_e32 v88, v88
	v_rcp_f32_e32 v89, v89
	v_rcp_f32_e32 v86, v86
	v_rcp_f32_e32 v87, v87
	v_rcp_f32_e32 v80, v80
	v_rcp_f32_e32 v81, v81
	v_rcp_f32_e32 v90, v90
	v_rcp_f32_e32 v91, v91
	v_mul_f32_e32 v82, v161, v161
	v_pk_mul_f32 v[88:89], v[82:83], v[88:89] op_sel_hi:[0,1]
	v_pk_mul_f32 v[86:87], v[82:83], v[86:87] op_sel_hi:[0,1]
	v_pk_mul_f32 v[80:81], v[82:83], v[80:81] op_sel_hi:[0,1]
	v_pk_mul_f32 v[82:83], v[82:83], v[90:91] op_sel_hi:[0,1]
	v_pk_mul_f32 v[70:71], v[70:71], v[86:87]
	v_pk_mul_f32 v[68:69], v[68:69], v[88:89]
	v_pk_mul_f32 v[72:73], v[66:67], v[82:83]
	v_pk_mul_f32 v[66:67], v[64:65], v[80:81]
	v_cvt_pk_bf16_f32 v64, v68, v69
	v_cvt_pk_bf16_f32 v65, v70, v71
	v_cvt_pk_bf16_f32 v66, v66, v67
	v_cvt_pk_bf16_f32 v67, v72, v73
	global_store_dwordx4 v[84:85], v[64:67], off offset:2048
	v_mul_f32_e32 v68, v173, v173
	s_nop 0
	v_mul_f32_e32 v66, 0xbfb8aa3b, v173
	v_pk_mul_f32 v[70:71], v[62:63], v[66:67] op_sel_hi:[1,0]
	v_pk_mul_f32 v[72:73], v[60:61], v[66:67] op_sel_hi:[1,0]
	v_pk_mul_f32 v[74:75], v[58:59], v[66:67] op_sel_hi:[1,0]
	v_pk_mul_f32 v[66:67], v[56:57], v[66:67] op_sel_hi:[1,0]
	v_exp_f32_e32 v70, v70
	v_exp_f32_e32 v71, v71
	v_exp_f32_e32 v72, v72
	v_exp_f32_e32 v73, v73
	v_exp_f32_e32 v66, v66
	v_exp_f32_e32 v74, v74
	v_exp_f32_e32 v75, v75
	v_exp_f32_e32 v67, v67
	v_pk_add_f32 v[70:71], v[70:71], 1.0 op_sel_hi:[1,0]
	v_pk_add_f32 v[72:73], v[72:73], 1.0 op_sel_hi:[1,0]
	v_pk_add_f32 v[74:75], v[74:75], 1.0 op_sel_hi:[1,0]
	v_pk_add_f32 v[66:67], v[66:67], 1.0 op_sel_hi:[1,0]
	v_rcp_f32_e32 v70, v70
	v_rcp_f32_e32 v71, v71
	v_rcp_f32_e32 v72, v72
	v_rcp_f32_e32 v73, v73
	v_rcp_f32_e32 v66, v66
	v_rcp_f32_e32 v67, v67
	v_rcp_f32_e32 v74, v74
	v_rcp_f32_e32 v75, v75
	v_lshrrev_b32_e32 v64, 8, v150
	v_mad_i32_i24 v64, v64, 44, s41
	v_pk_mul_f32 v[70:71], v[68:69], v[70:71] op_sel_hi:[0,1]
	v_ashrrev_i32_e32 v65, 31, v64
	v_pk_mul_f32 v[72:73], v[68:69], v[72:73] op_sel_hi:[0,1]
	v_pk_mul_f32 v[66:67], v[68:69], v[66:67] op_sel_hi:[0,1]
	v_pk_mul_f32 v[68:69], v[68:69], v[74:75] op_sel_hi:[0,1]
	v_pk_mul_f32 v[54:55], v[54:55], v[70:71]
	v_lshlrev_b64 v[64:65], 15, v[64:65]
	v_pk_mul_f32 v[52:53], v[52:53], v[72:73]
	v_pk_mul_f32 v[56:57], v[50:51], v[68:69]
	v_pk_mul_f32 v[50:51], v[48:49], v[66:67]
	v_cvt_pk_bf16_f32 v49, v54, v55
	v_lshlrev_b32_e32 v54, 7, v150
	v_cvt_pk_bf16_f32 v48, v52, v53
	v_lshl_add_u64 v[52:53], s[36:37], 0, v[64:65]
	v_and_b32_e32 v136, 0x6780, v54
	v_lshl_add_u64 v[52:53], v[52:53], 0, v[136:137]
	v_cvt_pk_bf16_f32 v50, v50, v51
	v_cvt_pk_bf16_f32 v51, v56, v57
	v_lshl_add_u64 v[52:53], v[52:53], 0, v[148:149]
	global_store_dwordx4 v[52:53], v[48:51], off
	s_nop 1
	v_mul_f32_e32 v48, 0xbfb8aa3b, v174
	v_pk_mul_f32 v[54:55], v[46:47], v[48:49] op_sel_hi:[1,0]
	v_pk_mul_f32 v[56:57], v[44:45], v[48:49] op_sel_hi:[1,0]
	v_pk_mul_f32 v[58:59], v[42:43], v[48:49] op_sel_hi:[1,0]
	v_pk_mul_f32 v[48:49], v[40:41], v[48:49] op_sel_hi:[1,0]
	v_exp_f32_e32 v56, v56
	v_exp_f32_e32 v57, v57
	v_exp_f32_e32 v54, v54
	v_exp_f32_e32 v55, v55
; #define PG8_BAR __builtin_amdgcn_s_barrier()
;     __device__ __forceinline__ void operator()(const f32x4 (&acc)[2][2][4][2], const Unit& u, int wr, int wc, int fr, int fq) const {
;     ...
;         for (int ai = 0; ai < 2; ++ai)
; #pragma unroll
;             for (int m = 0; m < 4; ++m) {
;                 const int row = row0 + ai * HALF + m * 16; const float rs = rsv[ai][m], cexp = -1.4426950408889634f * rs, rs2 = rs * rs;
;                 const f32x4 g0 = acc[ai][0][m][0], g1 = acc[ai][0][m][1], u0 = acc[ai][1][m][0], u1 = acc[ai][1][m][1];
;                 const f32x4 t0 = g0 * cexp, t1 = g1 * cexp;
;                 f32x4 d0 = (f32x4){__builtin_amdgcn_exp2f(t0[0]), __builtin_amdgcn_exp2f(t0[1]), __builtin_amdgcn_exp2f(t0[2]), __builtin_amdgcn_exp2f(t0[3])} + 1.0f;
;                 f32x4 d1 = (f32x4){__builtin_amdgcn_exp2f(t1[0]), __builtin_amdgcn_exp2f(t1[1]), __builtin_amdgcn_exp2f(t1[2]), __builtin_amdgcn_exp2f(t1[3])} + 1.0f;
;                 const f32x4 r0 = (f32x4){__builtin_amdgcn_rcpf(d0[0]), __builtin_amdgcn_rcpf(d0[1]), __builtin_amdgcn_rcpf(d0[2]), __builtin_amdgcn_rcpf(d0[3])} * rs2;
;                 const f32x4 r1 = (f32x4){__builtin_amdgcn_rcpf(d1[0]), __builtin_amdgcn_rcpf(d1[1]), __builtin_amdgcn_rcpf(d1[2]), __builtin_amdgcn_rcpf(d1[3])} * rs2;
;                 const f32x4 a0 = (g0 * u0) * r0, a1 = (g1 * u1) * r1;
;                 u32x4 w; w.x = cvt_pk_bf16(a0[0], a0[1]); w.y = cvt_pk_bf16(a0[2], a0[3]); w.z = cvt_pk_bf16(a1[0], a1[1]); w.w = cvt_pk_bf16(a1[2], a1[3]);
;                 *(u32x4*)(O + (((size_t)(row >> 8) * (DFF / BK) + (col0 >> 6)) * BM + (row & 255)) * BK + (col0 & 63)) = w;
; template <class Epi, class Sched, bool ALIGN_EPI = false, bool SP2 = false, bool ATILED = false>
; __device__ __forceinline__ void gemm_phase(PG8_LAS unsigned char* lds, const Gemm g, const Sched& S, const Epi& E) {
;     ...
;         if constexpr (!Epi::AFTER_DRAIN) { E(acc, cur, wr, wc, fr, fq); S.done(cur); }
;         if (!has_next) break;
; #pragma unroll
;         for (int a = 0; a < 2; ++a)
; #pragma unroll
;             for (int b = 0; b < 2; ++b)
; #pragma unroll
;                 for (int m = 0; m < 4; ++m)
; #pragma unroll
;                     for (int n = 0; n < 2; ++n) acc[a][b][m][n] = (f32x4){0.f, 0.f, 0.f, 0.f};
;         cur = nxt; cA = nA; cB = nB; ++ui;
;         if constexpr (ALIGN_EPI) { if (wr == 1) PG8_BAR; }
	v_exp_f32_e32 v48, v48
	v_exp_f32_e32 v58, v58
	v_exp_f32_e32 v59, v59
	v_exp_f32_e32 v49, v49
	v_pk_add_f32 v[54:55], v[54:55], 1.0 op_sel_hi:[1,0]
	v_pk_add_f32 v[56:57], v[56:57], 1.0 op_sel_hi:[1,0]
	v_pk_add_f32 v[58:59], v[58:59], 1.0 op_sel_hi:[1,0]
	v_pk_add_f32 v[48:49], v[48:49], 1.0 op_sel_hi:[1,0]
	v_rcp_f32_e32 v56, v56
	v_rcp_f32_e32 v57, v57
	v_rcp_f32_e32 v54, v54
	v_rcp_f32_e32 v55, v55
	v_rcp_f32_e32 v48, v48
	v_rcp_f32_e32 v49, v49
	v_rcp_f32_e32 v58, v58
	v_rcp_f32_e32 v59, v59
	v_mul_f32_e32 v50, v174, v174
	v_pk_mul_f32 v[56:57], v[50:51], v[56:57] op_sel_hi:[0,1]
	v_pk_mul_f32 v[54:55], v[50:51], v[54:55] op_sel_hi:[0,1]
	v_pk_mul_f32 v[48:49], v[50:51], v[48:49] op_sel_hi:[0,1]
	v_pk_mul_f32 v[50:51], v[50:51], v[58:59] op_sel_hi:[0,1]
	v_pk_mul_f32 v[38:39], v[38:39], v[54:55]
	v_pk_mul_f32 v[36:37], v[36:37], v[56:57]
	v_pk_mul_f32 v[40:41], v[34:35], v[50:51]
	v_pk_mul_f32 v[34:35], v[32:33], v[48:49]
	v_cvt_pk_bf16_f32 v32, v36, v37
	v_cvt_pk_bf16_f32 v33, v38, v39
	v_cvt_pk_bf16_f32 v34, v34, v35
	v_cvt_pk_bf16_f32 v35, v40, v41
	global_store_dwordx4 v[52:53], v[32:35], off offset:2048
	s_nop 1
	v_mul_f32_e32 v32, 0xbfb8aa3b, v175
	v_pk_mul_f32 v[38:39], v[28:29], v[32:33] op_sel_hi:[1,0]
	v_pk_mul_f32 v[36:37], v[30:31], v[32:33] op_sel_hi:[1,0]
	v_pk_mul_f32 v[40:41], v[26:27], v[32:33] op_sel_hi:[1,0]
	v_pk_mul_f32 v[32:33], v[24:25], v[32:33] op_sel_hi:[1,0]
	v_exp_f32_e32 v38, v38
	v_exp_f32_e32 v39, v39
	v_exp_f32_e32 v36, v36
	v_exp_f32_e32 v37, v37
	v_exp_f32_e32 v32, v32
	v_exp_f32_e32 v40, v40
	v_exp_f32_e32 v41, v41
	v_exp_f32_e32 v33, v33
	v_pk_add_f32 v[38:39], v[38:39], 1.0 op_sel_hi:[1,0]
	v_pk_add_f32 v[36:37], v[36:37], 1.0 op_sel_hi:[1,0]
	v_pk_add_f32 v[40:41], v[40:41], 1.0 op_sel_hi:[1,0]
	v_pk_add_f32 v[32:33], v[32:33], 1.0 op_sel_hi:[1,0]
	v_rcp_f32_e32 v38, v38
	v_rcp_f32_e32 v39, v39
	v_rcp_f32_e32 v36, v36
	v_rcp_f32_e32 v37, v37
	v_rcp_f32_e32 v32, v32
	v_rcp_f32_e32 v33, v33
	v_rcp_f32_e32 v40, v40
	v_rcp_f32_e32 v41, v41
	v_mul_f32_e32 v34, v175, v175
	v_pk_mul_f32 v[38:39], v[34:35], v[38:39] op_sel_hi:[0,1]
	v_pk_mul_f32 v[36:37], v[34:35], v[36:37] op_sel_hi:[0,1]
	v_pk_mul_f32 v[32:33], v[34:35], v[32:33] op_sel_hi:[0,1]
	v_pk_mul_f32 v[34:35], v[34:35], v[40:41] op_sel_hi:[0,1]
	v_pk_mul_f32 v[20:21], v[20:21], v[38:39]
	v_pk_mul_f32 v[22:23], v[22:23], v[36:37]
	v_pk_mul_f32 v[24:25], v[18:19], v[34:35]
	v_pk_mul_f32 v[18:19], v[16:17], v[32:33]
	v_cvt_pk_bf16_f32 v16, v20, v21
	v_add_co_u32_e32 v20, vcc, s80, v52
	v_cvt_pk_bf16_f32 v17, v22, v23
	v_cvt_pk_bf16_f32 v18, v18, v19
	v_cvt_pk_bf16_f32 v19, v24, v25
	v_addc_co_u32_e32 v21, vcc, 0, v53, vcc
	global_store_dwordx4 v[20:21], v[16:19], off
	s_andn2_b64 vcc, exec, s[0:1]
	s_mov_b64 s[0:1], -1
	v_mul_f32_e32 v16, 0xbfb8aa3b, v151
	v_pk_mul_f32 v[22:23], v[14:15], v[16:17] op_sel_hi:[1,0]
	v_pk_mul_f32 v[24:25], v[12:13], v[16:17] op_sel_hi:[1,0]
	v_pk_mul_f32 v[26:27], v[10:11], v[16:17] op_sel_hi:[1,0]
	v_pk_mul_f32 v[16:17], v[8:9], v[16:17] op_sel_hi:[1,0]
	v_exp_f32_e32 v24, v24
	v_exp_f32_e32 v25, v25
	v_exp_f32_e32 v22, v22
	v_exp_f32_e32 v23, v23
	v_exp_f32_e32 v16, v16
	v_exp_f32_e32 v26, v26
	v_exp_f32_e32 v27, v27
	v_exp_f32_e32 v17, v17
	v_pk_add_f32 v[22:23], v[22:23], 1.0 op_sel_hi:[1,0]
	v_pk_add_f32 v[24:25], v[24:25], 1.0 op_sel_hi:[1,0]
	v_pk_add_f32 v[26:27], v[26:27], 1.0 op_sel_hi:[1,0]
	v_pk_add_f32 v[16:17], v[16:17], 1.0 op_sel_hi:[1,0]
	v_rcp_f32_e32 v24, v24
	v_rcp_f32_e32 v25, v25
	v_rcp_f32_e32 v22, v22
	v_rcp_f32_e32 v23, v23
	v_rcp_f32_e32 v16, v16
	v_rcp_f32_e32 v17, v17
	v_rcp_f32_e32 v26, v26
	v_rcp_f32_e32 v27, v27
	v_mul_f32_e32 v18, v151, v151
	v_pk_mul_f32 v[24:25], v[18:19], v[24:25] op_sel_hi:[0,1]
	v_pk_mul_f32 v[22:23], v[18:19], v[22:23] op_sel_hi:[0,1]
	v_pk_mul_f32 v[16:17], v[18:19], v[16:17] op_sel_hi:[0,1]
	v_pk_mul_f32 v[18:19], v[18:19], v[26:27] op_sel_hi:[0,1]
	v_pk_mul_f32 v[6:7], v[6:7], v[22:23]
	v_pk_mul_f32 v[4:5], v[4:5], v[24:25]
	v_pk_mul_f32 v[8:9], v[2:3], v[18:19]
	v_pk_mul_f32 v[2:3], v[0:1], v[16:17]
	v_cvt_pk_bf16_f32 v0, v4, v5
	v_cvt_pk_bf16_f32 v1, v6, v7
	v_cvt_pk_bf16_f32 v2, v2, v3
	v_cvt_pk_bf16_f32 v3, v8, v9
	global_store_dwordx4 v[20:21], v[0:3], off offset:2048
	s_cbranch_vccnz .LBB0_129
	s_andn2_b64 vcc, exec, s[4:5]
	s_cbranch_vccnz .LBB0_128
	s_barrier
	s_branch .LBB0_128

; __device__ __forceinline__ unsigned cvt_pk_bf16(float lo, float hi) { typedef float f2 __attribute__((ext_vector_type(2))); const bf16v2 r = __builtin_convertvector((f2){lo, hi}, bf16v2); return __builtin_bit_cast(unsigned, r); }
;     __device__ __forceinline__ void operator()(const f32x4 (&acc)[2][2][4][2], const Unit& u, int wr, int wc, int fr, int fq) const {
;         const int row0 = u.pm * BM + wr * 64 + fr, col0 = u.pn * BM + wc * 32 + 8 * fq;
; #pragma unroll
;         for (int ai = 0; ai < 2; ++ai) {
;             u32x4 pre[4][2];
; #pragma unroll
;             for (int m = 0; m < 4; ++m)
; #pragma unroll
;                 for (int bj = 0; bj < 2; ++bj) pre[m][bj] = *(const u32x4*)(base + (size_t)(row0 + ai * HALF + m * 16) * DM + col0 + bj * HALF);
; #pragma unroll
;             for (int m = 0; m < 4; ++m) {
;                 const int row = row0 + ai * HALF + m * 16; float q = 0.f;
; #pragma unroll
;                 for (int bj = 0; bj < 2; ++bj) {
;                     const size_t off = (size_t)row * DM + col0 + bj * HALF;
;                     f32x4 b0, b1; bf8_to_f32(pre[m][bj], b0, b1);
;                     const f32x4 o0 = b0 + acc[ai][bj][m][0] * alpha, o1 = b1 + acc[ai][bj][m][1] * alpha;
;                     u32x4 w; w.x = cvt_pk_bf16(o0[0], o0[1]); w.y = cvt_pk_bf16(o0[2], o0[3]); w.z = cvt_pk_bf16(o1[0], o1[1]); w.w = cvt_pk_bf16(o1[2], o1[3]); *(u32x4*)(xb + off) = w;
;                     q += (o0[0] * o0[0] + o0[1] * o0[1]) + (o0[2] * o0[2] + o0[3] * o0[3]) + (o1[0] * o1[0] + o1[1] * o1[1]) + (o1[2] * o1[2] + o1[3] * o1[3]);
;                 }
;                 q += __shfl_xor(q, 16); q += __shfl_xor(q, 32);
;                 if (fq == 0) ssq[(size_t)row * 16 + u.pn * 4 + wc] = q;
.LBB0_214:
	v_lshl_or_b32 v168, s8, 8, v188
	v_lshl_add_u32 v170, s78, 8, v186
	v_ashrrev_i32_e32 v169, 31, v168
	v_lshlrev_b64 v[196:197], 1, v[168:169]
	v_ashrrev_i32_e32 v171, 31, v170
	v_lshl_add_u64 v[172:173], s[26:27], 0, v[196:197]
	v_lshlrev_b64 v[208:209], 11, v[170:171]
	v_lshl_add_u64 v[128:129], v[172:173], 0, v[208:209]
	global_load_dwordx4 v[200:203], v[128:129], off
	global_load_dwordx4 v[204:207], v[128:129], off offset:256
	v_or_b32_e32 v182, 16, v170
	v_or_b32_e32 v178, 32, v170
	v_or_b32_e32 v174, 48, v170
	v_ashrrev_i32_e32 v183, 31, v182
	v_ashrrev_i32_e32 v179, 31, v178
	v_ashrrev_i32_e32 v175, 31, v174
	v_lshlrev_b64 v[184:185], 11, v[182:183]
	v_lshlrev_b64 v[180:181], 11, v[178:179]
	v_lshlrev_b64 v[176:177], 11, v[174:175]
	v_lshl_add_u64 v[128:129], v[172:173], 0, v[184:185]
	v_lshl_add_u64 v[130:131], v[172:173], 0, v[180:181]
	v_lshl_add_u64 v[194:195], v[172:173], 0, v[176:177]
	global_load_dwordx4 v[148:151], v[128:129], off
	global_load_dwordx4 v[144:147], v[128:129], off offset:256
	global_load_dwordx4 v[140:143], v[130:131], off
	global_load_dwordx4 v[136:139], v[130:131], off offset:256
	global_load_dwordx4 v[132:135], v[194:195], off
	s_nop 0
	global_load_dwordx4 v[128:131], v[194:195], off offset:256
	v_and_b32_e32 v194, 64, v192
	v_xor_b32_e32 v193, 16, v192
	v_add_u32_e32 v194, 64, v194
	v_xor_b32_e32 v195, 32, v192
	v_cmp_lt_i32_e32 vcc, v193, v194
	s_lshl_b32 s46, s8, 2
	s_ashr_i32 s47, s46, 31
	v_cndmask_b32_e32 v193, v192, v193, vcc
	v_cmp_lt_i32_e32 vcc, v195, v194
	v_lshlrev_b32_e32 v194, 2, v193
	s_cmp_lg_u64 s[42:43], 0
	s_cbranch_scc0 .Lalign2_skip1
	s_barrier
.Lalign2_skip1:
	s_waitcnt vmcnt(0)
	v_lshlrev_b32_e32 v210, 16, v200
	v_and_b32_e32 v211, 0xffff0000, v200
	v_lshlrev_b32_e32 v200, 16, v201
	v_and_b32_e32 v201, 0xffff0000, v201
	v_lshlrev_b32_e32 v214, 16, v204
	v_and_b32_e32 v215, 0xffff0000, v204
	v_lshlrev_b32_e32 v204, 16, v205
	v_and_b32_e32 v205, 0xffff0000, v205
	v_cndmask_b32_e32 v195, v192, v195, vcc
	v_lshlrev_b32_e32 v212, 16, v202
	v_and_b32_e32 v213, 0xffff0000, v202
	v_lshlrev_b32_e32 v202, 16, v203
	v_and_b32_e32 v203, 0xffff0000, v203
	v_lshlrev_b32_e32 v216, 16, v206
	v_and_b32_e32 v217, 0xffff0000, v206
	v_pk_fma_f32 v[126:127], v[126:127], 0.5, v[200:201] op_sel_hi:[1,0,1]
	v_pk_fma_f32 v[124:125], v[124:125], 0.5, v[210:211] op_sel_hi:[1,0,1]
	v_pk_fma_f32 v[118:119], v[118:119], 0.5, v[204:205] op_sel_hi:[1,0,1]
	v_pk_fma_f32 v[116:117], v[116:117], 0.5, v[214:215] op_sel_hi:[1,0,1]
	v_lshlrev_b32_e32 v193, 2, v195
	v_lshlrev_b32_e32 v206, 16, v207
	v_and_b32_e32 v207, 0xffff0000, v207
	v_pk_fma_f32 v[122:123], v[122:123], 0.5, v[202:203] op_sel_hi:[1,0,1]
	v_pk_fma_f32 v[120:121], v[120:121], 0.5, v[212:213] op_sel_hi:[1,0,1]
	v_pk_fma_f32 v[202:203], v[112:113], 0.5, v[216:217] op_sel_hi:[1,0,1]
	v_cvt_pk_bf16_f32 v112, v124, v125
	v_cvt_pk_bf16_f32 v113, v126, v127
	v_mul_f32_e32 v125, v125, v125
	v_mul_f32_e32 v127, v127, v127
	v_mul_f32_e32 v195, v117, v117
	v_mul_f32_e32 v204, v119, v119
	v_pk_fma_f32 v[200:201], v[114:115], 0.5, v[206:207] op_sel_hi:[1,0,1]
	v_cvt_pk_bf16_f32 v114, v120, v121
	v_cvt_pk_bf16_f32 v115, v122, v123
	v_mul_f32_e32 v121, v121, v121
	v_mul_f32_e32 v123, v123, v123
	v_mul_f32_e32 v205, v203, v203
	v_fmac_f32_e32 v125, v124, v124
	v_fmac_f32_e32 v127, v126, v126
	v_fmac_f32_e32 v195, v116, v116
	v_fmac_f32_e32 v204, v118, v118
	v_mul_f32_e32 v206, v201, v201
	v_fmac_f32_e32 v121, v120, v120
	v_fmac_f32_e32 v123, v122, v122
	v_fmac_f32_e32 v205, v202, v202
	v_add_f32_e32 v120, v125, v127
	v_add_f32_e32 v122, v195, v204
	v_fmac_f32_e32 v206, v200, v200
	v_add_f32_e32 v120, v121, v120
	v_add_f32_e32 v121, v205, v122
	v_add_f32_e32 v120, v123, v120
	v_add_f32_e32 v121, v206, v121
	v_add_f32_e32 v122, v120, v121
	ds_bpermute_b32 v123, v194, v122
	v_lshl_add_u64 v[120:121], s[26:27], 0, v[208:209]
	v_lshl_add_u64 v[120:121], v[120:121], 0, v[196:197]
	global_store_dwordx4 v[120:121], v[112:115], off
	s_waitcnt lgkmcnt(0)
	s_nop 0
	v_add_f32_e32 v112, v122, v123
	ds_bpermute_b32 v113, v193, v112
	v_cvt_pk_bf16_f32 v114, v116, v117
	v_cvt_pk_bf16_f32 v115, v118, v119
	v_cvt_pk_bf16_f32 v116, v202, v203
	v_cvt_pk_bf16_f32 v117, v200, v201
	global_store_dwordx4 v[120:121], v[114:117], off offset:256
	s_and_saveexec_b64 s[48:49], s[0:1]
	s_cbranch_execz .LBB0_216
	v_lshlrev_b64 v[114:115], 6, v[170:171]
	v_lshl_add_u64 v[114:115], s[10:11], 0, v[114:115]
	v_lshl_add_u64 v[114:115], s[46:47], 2, v[114:115]
	s_lshl_b32 s8, s70, 2
	v_lshl_add_u64 v[114:115], v[114:115], 0, s[8:9]
	s_waitcnt lgkmcnt(0)
	v_add_f32_e32 v112, v112, v113
	global_store_dword v[114:115], v112, off

; __device__ __forceinline__ void rows_rstd(const float* ssq, int row0, int fq, float (&rs)[2][4]) {
;     f32x4 p[2][4];
; #pragma unroll
;     for (int ai = 0; ai < 2; ++ai)
; #pragma unroll
;         for (int m = 0; m < 4; ++m) p[ai][m] = *(const f32x4*)(ssq + (size_t)(row0 + ai * HALF + m * 16) * 16 + 4 * fq);
; #pragma unroll
;     for (int ai = 0; ai < 2; ++ai)
; #pragma unroll
;         for (int m = 0; m < 4; ++m) { float s = (p[ai][m][0] + p[ai][m][1]) + (p[ai][m][2] + p[ai][m][3]); s += __shfl_xor(s, 16); s += __shfl_xor(s, 32); rs[ai][m] = __builtin_amdgcn_rsqf(s * (1.0f / (float)DM) + RMS_EPS); }
; }
;     __device__ __forceinline__ void operator()(const f32x4 (&acc)[2][2][4][2], const Unit& u, int wr, int wc, int fr, int fq) const {
;         const int row0 = u.pm * BM + wr * 64 + fr, pn = u.pn;
;         float rsv[2][4]; rows_rstd(ssq, row0, fq, rsv);
;         if (pn < 2) {
.LBB0_303:
	v_lshl_add_u32 v166, s4, 8, v139
	v_or_b32_e32 v180, 16, v166
	v_ashrrev_i32_e32 v167, 31, v166
	v_ashrrev_i32_e32 v181, 31, v180
	v_lshlrev_b64 v[156:157], 6, v[166:167]
	v_lshlrev_b64 v[158:159], 6, v[180:181]
	v_or_b32_e32 v176, 32, v166
	v_or_b32_e32 v170, 48, v166
	v_lshl_add_u64 v[156:157], v[140:141], 0, v[156:157]
	v_lshl_add_u64 v[158:159], v[140:141], 0, v[158:159]
	v_ashrrev_i32_e32 v177, 31, v176
	v_ashrrev_i32_e32 v171, 31, v170
	global_load_dwordx4 v[172:175], v[156:157], off
	global_load_dwordx4 v[182:185], v[158:159], off
	v_lshlrev_b64 v[156:157], 6, v[176:177]
	v_lshlrev_b64 v[158:159], 6, v[170:171]
	v_lshl_add_u64 v[156:157], v[140:141], 0, v[156:157]
	v_lshl_add_u64 v[158:159], v[140:141], 0, v[158:159]
	global_load_dwordx4 v[186:189], v[156:157], off
	global_load_dwordx4 v[190:193], v[158:159], off
	v_add_u32_e32 v164, 0x80, v166
	v_add_u32_e32 v158, 0xa0, v166
	v_ashrrev_i32_e32 v165, 31, v164
	v_ashrrev_i32_e32 v159, 31, v158
	v_lshlrev_b64 v[156:157], 6, v[164:165]
	v_add_u32_e32 v160, 0x90, v166
	v_lshlrev_b64 v[162:163], 6, v[158:159]
	v_lshl_add_u64 v[156:157], v[140:141], 0, v[156:157]
	v_ashrrev_i32_e32 v161, 31, v160
	v_lshl_add_u64 v[162:163], v[140:141], 0, v[162:163]
	global_load_dwordx4 v[194:197], v[156:157], off
	global_load_dwordx4 v[212:215], v[162:163], off
	v_lshlrev_b64 v[156:157], 6, v[160:161]
	v_lshl_add_u64 v[156:157], v[140:141], 0, v[156:157]
	global_load_dwordx4 v[208:211], v[156:157], off
	v_add_u32_e32 v156, 0xb0, v166
	v_ashrrev_i32_e32 v157, 31, v156
	v_lshlrev_b64 v[162:163], 6, v[156:157]
	v_lshl_add_u64 v[162:163], v[140:141], 0, v[162:163]
	global_load_dwordx4 v[216:219], v[162:163], off
	v_and_b32_e32 v155, 64, v204
	v_xor_b32_e32 v136, 16, v204
	v_add_u32_e32 v155, 64, v155
	v_xor_b32_e32 v162, 32, v204
	v_cmp_lt_i32_e32 vcc, v136, v155
	s_cmp_lg_u64 s[40:41], 0
	s_cbranch_scc0 .Lalign2_skip2
	s_barrier
.Lalign2_skip2:
	s_cmp_gt_i32 s62, 1
	s_mov_b64 s[4:5], -1
	v_cndmask_b32_e32 v136, v204, v136, vcc
	v_cmp_lt_i32_e32 vcc, v162, v155
	v_lshlrev_b32_e32 v136, 2, v136
	s_waitcnt vmcnt(0)
	v_add_f32_e32 v163, v174, v175
	v_cndmask_b32_e32 v155, v204, v162, vcc
	v_add_f32_e32 v162, v172, v173
	v_add_f32_e32 v162, v162, v163
	v_add_f32_e32 v163, v182, v183
	v_add_f32_e32 v168, v184, v185
	v_add_f32_e32 v169, v186, v187
	v_add_f32_e32 v172, v188, v189
	v_add_f32_e32 v173, v190, v191
	v_add_f32_e32 v174, v192, v193
	ds_bpermute_b32 v183, v136, v162
	v_add_f32_e32 v163, v163, v168
	v_add_f32_e32 v168, v169, v172
	v_add_f32_e32 v169, v173, v174
	ds_bpermute_b32 v174, v136, v163
	v_lshlrev_b32_e32 v155, 2, v155
	s_waitcnt lgkmcnt(1)
	v_add_f32_e32 v162, v162, v183
	v_add_f32_e32 v175, v194, v195
	v_add_f32_e32 v178, v196, v197
	v_add_f32_e32 v172, v175, v178
	ds_bpermute_b32 v175, v136, v168
	v_add_f32_e32 v179, v208, v209
	v_add_f32_e32 v182, v210, v211
	v_add_f32_e32 v173, v179, v182
	ds_bpermute_b32 v178, v136, v169
	ds_bpermute_b32 v179, v136, v172
	ds_bpermute_b32 v183, v155, v162
	s_waitcnt lgkmcnt(4)
	v_add_f32_e32 v163, v163, v174
	s_waitcnt lgkmcnt(3)
	v_add_f32_e32 v168, v168, v175
	s_waitcnt lgkmcnt(2)
	v_add_f32_e32 v169, v169, v178
	s_waitcnt lgkmcnt(1)
	v_add_f32_e32 v172, v172, v179
	ds_bpermute_b32 v174, v155, v163
	ds_bpermute_b32 v175, v155, v168
	ds_bpermute_b32 v178, v155, v169
	ds_bpermute_b32 v179, v155, v172
	ds_bpermute_b32 v182, v136, v173
	s_waitcnt lgkmcnt(5)
	v_add_f32_e32 v162, v162, v183
	v_fmamk_f32 v162, v162, 0x3a800000, v205
	s_waitcnt lgkmcnt(4)
	v_add_f32_e32 v163, v163, v174
	s_waitcnt lgkmcnt(3)
	v_add_f32_e32 v168, v168, v175
	s_waitcnt lgkmcnt(2)
	v_add_f32_e32 v169, v169, v178
	s_waitcnt lgkmcnt(1)
	v_add_f32_e32 v172, v172, v179
	v_rsq_f32_e32 v184, v162
	v_fmamk_f32 v162, v163, 0x3a800000, v205
	v_fmamk_f32 v163, v168, 0x3a800000, v205
	v_fmamk_f32 v168, v169, 0x3a800000, v205
	v_fmamk_f32 v169, v172, 0x3a800000, v205
	s_waitcnt lgkmcnt(0)
	v_add_f32_e32 v173, v173, v182
	v_rsq_f32_e32 v186, v162
	v_rsq_f32_e32 v182, v163
	v_rsq_f32_e32 v178, v168
	v_rsq_f32_e32 v174, v169
	v_add_f32_e32 v162, v212, v213
	v_add_f32_e32 v163, v214, v215
	v_add_f32_e32 v168, v216, v217
	v_add_f32_e32 v169, v218, v219
	v_add_f32_e32 v162, v162, v163
	v_add_f32_e32 v168, v168, v169
	ds_bpermute_b32 v163, v136, v162
	ds_bpermute_b32 v136, v136, v168
	ds_bpermute_b32 v185, v155, v173
	s_waitcnt lgkmcnt(2)
	v_add_f32_e32 v162, v162, v163
	s_waitcnt lgkmcnt(1)
	v_add_f32_e32 v136, v168, v136
	ds_bpermute_b32 v163, v155, v162
	ds_bpermute_b32 v155, v155, v136
	s_waitcnt lgkmcnt(2)
	v_add_f32_e32 v169, v173, v185
	v_fmamk_f32 v169, v169, 0x3a800000, v205
	v_rsq_f32_e32 v172, v169
	s_waitcnt lgkmcnt(1)
	v_add_f32_e32 v162, v162, v163
	s_waitcnt lgkmcnt(0)
	v_add_f32_e32 v136, v136, v155
	v_fmamk_f32 v162, v162, 0x3a800000, v205
	v_fmamk_f32 v136, v136, 0x3a800000, v205
	v_rsq_f32_e32 v168, v162
	v_rsq_f32_e32 v162, v136
	s_cbranch_scc1 .LBB0_306
	s_and_b64 vcc, exec, s[4:5]
	s_cbranch_vccnz .LBB0_339

; __device__ __forceinline__ unsigned cvt_pk_bf16(float lo, float hi) { typedef float f2 __attribute__((ext_vector_type(2))); const bf16v2 r = __builtin_convertvector((f2){lo, hi}, bf16v2); return __builtin_bit_cast(unsigned, r); }
;     __device__ __forceinline__ void operator()(const f32x4 (&acc)[2][2][4][2], const Unit& u, int wr, int wc, int fr, int fq) const {
;         const int row0 = u.pm * BM + wr * 64 + fr, col0 = u.pn * BM + wc * 32 + 8 * fq;
; #pragma unroll
;         for (int ai = 0; ai < 2; ++ai) {
;             u32x4 pre[4][2];
; #pragma unroll
;             for (int m = 0; m < 4; ++m)
; #pragma unroll
;                 for (int bj = 0; bj < 2; ++bj) pre[m][bj] = *(const u32x4*)(base + (size_t)(row0 + ai * HALF + m * 16) * DM + col0 + bj * HALF);
; #pragma unroll
;             for (int m = 0; m < 4; ++m) {
;                 const int row = row0 + ai * HALF + m * 16; float q = 0.f;
; #pragma unroll
;                 for (int bj = 0; bj < 2; ++bj) {
;                     const size_t off = (size_t)row * DM + col0 + bj * HALF;
;                     f32x4 b0, b1; bf8_to_f32(pre[m][bj], b0, b1);
;                     const f32x4 o0 = b0 + acc[ai][bj][m][0] * alpha, o1 = b1 + acc[ai][bj][m][1] * alpha;
;                     u32x4 w; w.x = cvt_pk_bf16(o0[0], o0[1]); w.y = cvt_pk_bf16(o0[2], o0[3]); w.z = cvt_pk_bf16(o1[0], o1[1]); w.w = cvt_pk_bf16(o1[2], o1[3]); *(u32x4*)(xb + off) = w;
;                     q += (o0[0] * o0[0] + o0[1] * o0[1]) + (o0[2] * o0[2] + o0[3] * o0[3]) + (o1[0] * o1[0] + o1[1] * o1[1]) + (o1[2] * o1[2] + o1[3] * o1[3]);
;                 }
;                 q += __shfl_xor(q, 16); q += __shfl_xor(q, 32);
;                 if (fq == 0) ssq[(size_t)row * 16 + u.pn * 4 + wc] = q;
.LBB0_738:
	v_lshl_or_b32 v168, s6, 8, v188
	v_lshl_add_u32 v170, s48, 8, v186
	v_ashrrev_i32_e32 v169, 31, v168
	v_lshlrev_b64 v[196:197], 1, v[168:169]
	v_ashrrev_i32_e32 v171, 31, v170
	v_lshl_add_u64 v[172:173], s[26:27], 0, v[196:197]
	v_lshlrev_b64 v[208:209], 11, v[170:171]
	v_lshl_add_u64 v[128:129], v[172:173], 0, v[208:209]
	global_load_dwordx4 v[200:203], v[128:129], off
	global_load_dwordx4 v[204:207], v[128:129], off offset:256
	v_or_b32_e32 v182, 16, v170
	v_or_b32_e32 v178, 32, v170
	v_or_b32_e32 v174, 48, v170
	v_ashrrev_i32_e32 v183, 31, v182
	v_ashrrev_i32_e32 v179, 31, v178
	v_ashrrev_i32_e32 v175, 31, v174
	v_lshlrev_b64 v[184:185], 11, v[182:183]
	v_lshlrev_b64 v[180:181], 11, v[178:179]
	v_lshlrev_b64 v[176:177], 11, v[174:175]
	v_lshl_add_u64 v[128:129], v[172:173], 0, v[184:185]
	v_lshl_add_u64 v[130:131], v[172:173], 0, v[180:181]
	v_lshl_add_u64 v[194:195], v[172:173], 0, v[176:177]
	global_load_dwordx4 v[148:151], v[128:129], off
	global_load_dwordx4 v[144:147], v[128:129], off offset:256
	global_load_dwordx4 v[140:143], v[130:131], off
	global_load_dwordx4 v[136:139], v[130:131], off offset:256
	global_load_dwordx4 v[132:135], v[194:195], off
	s_nop 0
	global_load_dwordx4 v[128:131], v[194:195], off offset:256
	v_and_b32_e32 v194, 64, v192
	v_xor_b32_e32 v193, 16, v192
	v_add_u32_e32 v194, 64, v194
	v_xor_b32_e32 v195, 32, v192
	v_cmp_lt_i32_e32 vcc, v193, v194
	s_lshl_b32 s48, s6, 2
	s_ashr_i32 s49, s48, 31
	v_cndmask_b32_e32 v193, v192, v193, vcc
	v_cmp_lt_i32_e32 vcc, v195, v194
	v_lshlrev_b32_e32 v194, 2, v193
	s_cmp_lg_u64 s[14:15], 0
	s_cbranch_scc0 .Lalign2_skip3
	s_barrier
.Lalign2_skip3:
	s_waitcnt vmcnt(0)
	v_lshlrev_b32_e32 v210, 16, v200
	v_and_b32_e32 v211, 0xffff0000, v200
	v_lshlrev_b32_e32 v200, 16, v201
	v_and_b32_e32 v201, 0xffff0000, v201
	v_lshlrev_b32_e32 v214, 16, v204
	v_and_b32_e32 v215, 0xffff0000, v204
	v_lshlrev_b32_e32 v204, 16, v205
	v_and_b32_e32 v205, 0xffff0000, v205
	v_cndmask_b32_e32 v195, v192, v195, vcc
	v_lshlrev_b32_e32 v212, 16, v202
	v_and_b32_e32 v213, 0xffff0000, v202
	v_lshlrev_b32_e32 v202, 16, v203
	v_and_b32_e32 v203, 0xffff0000, v203
	v_lshlrev_b32_e32 v216, 16, v206
	v_and_b32_e32 v217, 0xffff0000, v206
	v_pk_add_f32 v[126:127], v[126:127], v[200:201]
	v_pk_add_f32 v[124:125], v[124:125], v[210:211]
	v_pk_add_f32 v[118:119], v[118:119], v[204:205]
	v_pk_add_f32 v[116:117], v[116:117], v[214:215]
	v_lshlrev_b32_e32 v193, 2, v195
	v_lshlrev_b32_e32 v206, 16, v207
	v_and_b32_e32 v207, 0xffff0000, v207
	v_pk_add_f32 v[122:123], v[122:123], v[202:203]
	v_pk_add_f32 v[120:121], v[120:121], v[212:213]
	v_pk_add_f32 v[202:203], v[112:113], v[216:217]
	v_cvt_pk_bf16_f32 v112, v124, v125
	v_cvt_pk_bf16_f32 v113, v126, v127
	v_mul_f32_e32 v125, v125, v125
	v_mul_f32_e32 v127, v127, v127
	v_mul_f32_e32 v195, v117, v117
	v_mul_f32_e32 v204, v119, v119
	v_pk_add_f32 v[200:201], v[114:115], v[206:207]
	v_cvt_pk_bf16_f32 v114, v120, v121
	v_cvt_pk_bf16_f32 v115, v122, v123
	v_mul_f32_e32 v121, v121, v121
	v_mul_f32_e32 v123, v123, v123
	v_mul_f32_e32 v205, v203, v203
	v_fmac_f32_e32 v125, v124, v124
	v_fmac_f32_e32 v127, v126, v126
	v_fmac_f32_e32 v195, v116, v116
	v_fmac_f32_e32 v204, v118, v118
	v_mul_f32_e32 v206, v201, v201
	v_fmac_f32_e32 v121, v120, v120
	v_fmac_f32_e32 v123, v122, v122
	v_fmac_f32_e32 v205, v202, v202
	v_add_f32_e32 v120, v125, v127
	v_add_f32_e32 v122, v195, v204
	v_fmac_f32_e32 v206, v200, v200
	v_add_f32_e32 v120, v121, v120
	v_add_f32_e32 v121, v205, v122
	v_add_f32_e32 v120, v123, v120
	v_add_f32_e32 v121, v206, v121
	v_add_f32_e32 v122, v120, v121
	ds_bpermute_b32 v123, v194, v122
	v_lshl_add_u64 v[120:121], s[26:27], 0, v[208:209]
	v_lshl_add_u64 v[120:121], v[120:121], 0, v[196:197]
	global_store_dwordx4 v[120:121], v[112:115], off
	s_waitcnt lgkmcnt(0)
	s_nop 0
	v_add_f32_e32 v112, v122, v123
	ds_bpermute_b32 v113, v193, v112
	v_cvt_pk_bf16_f32 v114, v116, v117
	v_cvt_pk_bf16_f32 v115, v118, v119
	v_cvt_pk_bf16_f32 v116, v202, v203
	v_cvt_pk_bf16_f32 v117, v200, v201
	global_store_dwordx4 v[120:121], v[114:117], off offset:256
	s_and_saveexec_b64 s[50:51], s[0:1]
	s_cbranch_execz .LBB0_740
	v_lshlrev_b64 v[114:115], 6, v[170:171]
	v_lshl_add_u64 v[114:115], s[10:11], 0, v[114:115]
	v_lshl_add_u64 v[114:115], s[48:49], 2, v[114:115]
	s_lshl_b32 s6, s62, 2
	v_lshl_add_u64 v[114:115], v[114:115], 0, s[6:7]
	s_waitcnt lgkmcnt(0)
	v_add_f32_e32 v112, v112, v113
	global_store_dword v[114:115], v112, off

; __device__ __forceinline__ void rows_rstd(const float* ssq, int row0, int fq, float (&rs)[2][4]) {
;     f32x4 p[2][4];
; #pragma unroll
;     for (int ai = 0; ai < 2; ++ai)
; #pragma unroll
;         for (int m = 0; m < 4; ++m) p[ai][m] = *(const f32x4*)(ssq + (size_t)(row0 + ai * HALF + m * 16) * 16 + 4 * fq);
; #pragma unroll
;     for (int ai = 0; ai < 2; ++ai)
; #pragma unroll
;         for (int m = 0; m < 4; ++m) { float s = (p[ai][m][0] + p[ai][m][1]) + (p[ai][m][2] + p[ai][m][3]); s += __shfl_xor(s, 16); s += __shfl_xor(s, 32); rs[ai][m] = __builtin_amdgcn_rsqf(s * (1.0f / (float)DM) + RMS_EPS); }
; }
;     __device__ __forceinline__ void operator()(const f32x4 (&acc)[2][2][4][2], const Unit& u, int wr, int wc, int fr, int fq) const {
;         const int row0 = u.pm * BM + wr * 64 + fr, col0 = u.pn * HALF + wc * 32 + 8 * fq;
;         float rsv[2][4]; rows_rstd(ssq, row0, fq, rsv);
; #pragma unroll
;         for (int ai = 0; ai < 2; ++ai)
; #pragma unroll
;             for (int m = 0; m < 4; ++m) {
;                 const int row = row0 + ai * HALF + m * 16; const float rs = rsv[ai][m], cexp = -1.4426950408889634f * rs, rs2 = rs * rs;
;                 const f32x4 g0 = acc[ai][0][m][0], g1 = acc[ai][0][m][1], u0 = acc[ai][1][m][0], u1 = acc[ai][1][m][1];
;                 const f32x4 t0 = g0 * cexp, t1 = g1 * cexp;
;                 f32x4 d0 = (f32x4){__builtin_amdgcn_exp2f(t0[0]), __builtin_amdgcn_exp2f(t0[1]), __builtin_amdgcn_exp2f(t0[2]), __builtin_amdgcn_exp2f(t0[3])} + 1.0f;
;                 f32x4 d1 = (f32x4){__builtin_amdgcn_exp2f(t1[0]), __builtin_amdgcn_exp2f(t1[1]), __builtin_amdgcn_exp2f(t1[2]), __builtin_amdgcn_exp2f(t1[3])} + 1.0f;
;                 const f32x4 r0 = (f32x4){__builtin_amdgcn_rcpf(d0[0]), __builtin_amdgcn_rcpf(d0[1]), __builtin_amdgcn_rcpf(d0[2]), __builtin_amdgcn_rcpf(d0[3])} * rs2;
;                 const f32x4 r1 = (f32x4){__builtin_amdgcn_rcpf(d1[0]), __builtin_amdgcn_rcpf(d1[1]), __builtin_amdgcn_rcpf(d1[2]), __builtin_amdgcn_rcpf(d1[3])} * rs2;
;                 const f32x4 a0 = (g0 * u0) * r0, a1 = (g1 * u1) * r1;
;                 u32x4 w; w.x = cvt_pk_bf16(a0[0], a0[1]); w.y = cvt_pk_bf16(a0[2], a0[3]); w.z = cvt_pk_bf16(a1[0], a1[1]); w.w = cvt_pk_bf16(a1[2], a1[3]);
;                 *(u32x4*)(O + (((size_t)(row >> 8) * (DFF / BK) + (col0 >> 6)) * BM + (row & 255)) * BK + (col0 & 63)) = w;
.LBB0_820:
	s_lshl_b32 s13, s18, 8
	s_add_i32 s13, s13, s56
	v_or_b32_e32 v152, s13, v154
	v_ashrrev_i32_e32 v153, 31, v152
	v_lshlrev_b64 v[150:151], 6, v[152:153]
	v_lshl_add_u64 v[182:183], v[138:139], 0, v[150:151]
	v_or_b32_e32 v150, 16, v152
	v_ashrrev_i32_e32 v151, 31, v150
	v_lshlrev_b64 v[150:151], 6, v[150:151]
	v_lshl_add_u64 v[150:151], v[138:139], 0, v[150:151]
	global_load_dwordx4 v[162:165], v[182:183], off
	global_load_dwordx4 v[166:169], v[150:151], off
	v_or_b32_e32 v150, 32, v152
	v_or_b32_e32 v170, 48, v152
	v_ashrrev_i32_e32 v151, 31, v150
	v_ashrrev_i32_e32 v171, 31, v170
	v_lshlrev_b64 v[150:151], 6, v[150:151]
	v_lshlrev_b64 v[170:171], 6, v[170:171]
	v_lshl_add_u64 v[150:151], v[138:139], 0, v[150:151]
	v_lshl_add_u64 v[174:175], v[138:139], 0, v[170:171]
	global_load_dwordx4 v[170:173], v[150:151], off
	s_nop 0
	global_load_dwordx4 v[174:177], v[174:175], off
	v_add_u32_e32 v150, 0x80, v152
	v_ashrrev_i32_e32 v151, 31, v150
	v_lshlrev_b64 v[178:179], 6, v[150:151]
	v_lshl_add_u64 v[178:179], v[138:139], 0, v[178:179]
	global_load_dwordx4 v[178:181], v[178:179], off
	v_add_co_u32_e32 v190, vcc, s51, v182
	v_and_b32_e32 v149, 64, v159
	s_nop 0
	v_addc_co_u32_e32 v191, vcc, 0, v183, vcc
	global_load_dwordx4 v[182:185], v[190:191], off offset:1024
	global_load_dwordx4 v[186:189], v[190:191], off offset:2048
	v_xor_b32_e32 v136, 16, v159
	global_load_dwordx4 v[190:193], v[190:191], off offset:3072
	v_add_u32_e32 v149, 64, v149
	v_xor_b32_e32 v151, 32, v159
	v_cmp_lt_i32_e32 vcc, v136, v149
	s_lshl_b32 s11, s63, 7
	s_or_b32 s11, s11, s57
	v_cndmask_b32_e32 v136, v159, v136, vcc
	v_cmp_lt_i32_e32 vcc, v151, v149
	v_lshlrev_b32_e32 v136, 2, v136
	s_ashr_i32 s13, s13, 8
	v_cndmask_b32_e32 v149, v159, v151, vcc
	v_lshlrev_b32_e32 v149, 2, v149
	s_ashr_i32 s11, s11, 6
	s_mul_i32 s13, s13, 44
	s_add_i32 s20, s13, s11
	s_ashr_i32 s21, s20, 31
	v_pk_mul_f32 v[116:117], v[124:125], v[116:117]
	s_lshl_b64 s[20:21], s[20:21], 15
	v_pk_mul_f32 v[114:115], v[122:123], v[114:115]
	v_pk_mul_f32 v[112:113], v[120:121], v[112:113]
	s_add_u32 s20, s36, s20
	v_pk_mul_f32 v[118:119], v[126:127], v[118:119]
	s_addc_u32 s21, s37, s21
	v_pk_mul_f32 v[102:103], v[110:111], v[102:103]
	v_pk_mul_f32 v[100:101], v[108:109], v[100:101]
	v_pk_mul_f32 v[98:99], v[106:107], v[98:99]
	v_pk_mul_f32 v[96:97], v[104:105], v[96:97]
	v_pk_mul_f32 v[84:85], v[92:93], v[84:85]
	v_pk_mul_f32 v[86:87], v[94:95], v[86:87]
	v_pk_mul_f32 v[82:83], v[90:91], v[82:83]
	v_pk_mul_f32 v[80:81], v[88:89], v[80:81]
	v_pk_mul_f32 v[70:71], v[78:79], v[70:71]
	v_pk_mul_f32 v[68:69], v[76:77], v[68:69]
	v_pk_mul_f32 v[66:67], v[74:75], v[66:67]
	v_pk_mul_f32 v[64:65], v[72:73], v[64:65]
	v_pk_mul_f32 v[54:55], v[62:63], v[54:55]
	v_pk_mul_f32 v[52:53], v[60:61], v[52:53]
	v_pk_mul_f32 v[50:51], v[58:59], v[50:51]
	v_pk_mul_f32 v[48:49], v[56:57], v[48:49]
	v_pk_mul_f32 v[38:39], v[46:47], v[38:39]
	v_pk_mul_f32 v[36:37], v[44:45], v[36:37]
	v_pk_mul_f32 v[34:35], v[42:43], v[34:35]
	v_pk_mul_f32 v[32:33], v[40:41], v[32:33]
	v_pk_mul_f32 v[20:21], v[28:29], v[20:21]
	v_pk_mul_f32 v[22:23], v[30:31], v[22:23]
	v_pk_mul_f32 v[18:19], v[26:27], v[18:19]
	v_pk_mul_f32 v[16:17], v[24:25], v[16:17]
	v_pk_mul_f32 v[6:7], v[14:15], v[6:7]
	v_pk_mul_f32 v[4:5], v[12:13], v[4:5]
	v_pk_mul_f32 v[2:3], v[10:11], v[2:3]
	v_pk_mul_f32 v[0:1], v[8:9], v[0:1]
	s_cmp_lg_u64 s[8:9], 0
	s_cbranch_scc0 .Lalign2_skip4
	s_barrier
.Lalign2_skip4:
	s_waitcnt vmcnt(0)
	v_mov_b32_e32 v194, v163
	v_mov_b32_e32 v195, v164
	v_mov_b32_e32 v163, v165
	v_pk_add_f32 v[162:163], v[194:195], v[162:163]
	v_mov_b32_e32 v164, v167
	v_mov_b32_e32 v165, v168
	v_mov_b32_e32 v167, v169
	v_add_f32_e32 v151, v162, v163
	v_pk_add_f32 v[162:163], v[164:165], v[166:167]
	v_mov_b32_e32 v168, v171
	v_mov_b32_e32 v169, v172
	v_mov_b32_e32 v171, v173
	v_mov_b32_e32 v172, v175
	v_mov_b32_e32 v173, v176
	v_mov_b32_e32 v175, v177
	v_mov_b32_e32 v176, v179
	v_mov_b32_e32 v177, v180
	v_mov_b32_e32 v179, v181
	v_pk_add_f32 v[164:165], v[168:169], v[170:171]
	v_pk_add_f32 v[166:167], v[172:173], v[174:175]
	ds_bpermute_b32 v153, v136, v151
	v_add_f32_e32 v161, v162, v163
	v_pk_add_f32 v[168:169], v[176:177], v[178:179]
	v_add_f32_e32 v162, v164, v165
	v_add_f32_e32 v163, v166, v167
	ds_bpermute_b32 v166, v136, v161
	v_add_f32_e32 v164, v168, v169
	ds_bpermute_b32 v167, v136, v162
	ds_bpermute_b32 v168, v136, v163
	ds_bpermute_b32 v169, v136, v164
	s_waitcnt lgkmcnt(4)
	v_add_f32_e32 v151, v151, v153
	ds_bpermute_b32 v153, v149, v151
	s_waitcnt lgkmcnt(4)
	v_add_f32_e32 v161, v161, v166
	s_waitcnt lgkmcnt(3)
	v_add_f32_e32 v162, v162, v167
	s_waitcnt lgkmcnt(2)
	v_add_f32_e32 v163, v163, v168
	ds_bpermute_b32 v166, v149, v161
	v_mov_b32_e32 v180, v183
	v_mov_b32_e32 v181, v184
	v_mov_b32_e32 v183, v185
	s_waitcnt lgkmcnt(2)
	v_add_f32_e32 v164, v164, v169
	ds_bpermute_b32 v167, v149, v162
	ds_bpermute_b32 v168, v149, v163
	v_pk_add_f32 v[170:171], v[180:181], v[182:183]
	ds_bpermute_b32 v169, v149, v164
	v_add_f32_e32 v165, v170, v171
	ds_bpermute_b32 v170, v136, v165
	s_waitcnt lgkmcnt(5)
	v_add_f32_e32 v151, v151, v153
	v_fmamk_f32 v151, v151, 0x3a800000, v160
	s_waitcnt lgkmcnt(4)
	v_add_f32_e32 v153, v161, v166
	s_waitcnt lgkmcnt(3)
	v_add_f32_e32 v161, v162, v167
	s_waitcnt lgkmcnt(2)
	v_add_f32_e32 v162, v163, v168
	v_rsq_f32_e32 v166, v151
	v_fmamk_f32 v151, v153, 0x3a800000, v160
	v_fmamk_f32 v153, v161, 0x3a800000, v160
	v_fmamk_f32 v161, v162, 0x3a800000, v160
	v_rsq_f32_e32 v172, v151
	s_waitcnt lgkmcnt(1)
; __device__ __forceinline__ unsigned cvt_pk_bf16(float lo, float hi) { typedef float f2 __attribute__((ext_vector_type(2))); const bf16v2 r = __builtin_convertvector((f2){lo, hi}, bf16v2); return __builtin_bit_cast(unsigned, r); }
;     __device__ __forceinline__ void operator()(const f32x4 (&acc)[2][2][4][2], const Unit& u, int wr, int wc, int fr, int fq) const {
;     ...
;         for (int ai = 0; ai < 2; ++ai)
; #pragma unroll
;             for (int m = 0; m < 4; ++m) {
;                 const int row = row0 + ai * HALF + m * 16; const float rs = rsv[ai][m], cexp = -1.4426950408889634f * rs, rs2 = rs * rs;
;                 const f32x4 g0 = acc[ai][0][m][0], g1 = acc[ai][0][m][1], u0 = acc[ai][1][m][0], u1 = acc[ai][1][m][1];
;                 const f32x4 t0 = g0 * cexp, t1 = g1 * cexp;
;                 f32x4 d0 = (f32x4){__builtin_amdgcn_exp2f(t0[0]), __builtin_amdgcn_exp2f(t0[1]), __builtin_amdgcn_exp2f(t0[2]), __builtin_amdgcn_exp2f(t0[3])} + 1.0f;
;                 f32x4 d1 = (f32x4){__builtin_amdgcn_exp2f(t1[0]), __builtin_amdgcn_exp2f(t1[1]), __builtin_amdgcn_exp2f(t1[2]), __builtin_amdgcn_exp2f(t1[3])} + 1.0f;
;                 const f32x4 r0 = (f32x4){__builtin_amdgcn_rcpf(d0[0]), __builtin_amdgcn_rcpf(d0[1]), __builtin_amdgcn_rcpf(d0[2]), __builtin_amdgcn_rcpf(d0[3])} * rs2;
;                 const f32x4 r1 = (f32x4){__builtin_amdgcn_rcpf(d1[0]), __builtin_amdgcn_rcpf(d1[1]), __builtin_amdgcn_rcpf(d1[2]), __builtin_amdgcn_rcpf(d1[3])} * rs2;
;                 const f32x4 a0 = (g0 * u0) * r0, a1 = (g1 * u1) * r1;
;                 u32x4 w; w.x = cvt_pk_bf16(a0[0], a0[1]); w.y = cvt_pk_bf16(a0[2], a0[3]); w.z = cvt_pk_bf16(a1[0], a1[1]); w.w = cvt_pk_bf16(a1[2], a1[3]);
;                 *(u32x4*)(O + (((size_t)(row >> 8) * (DFF / BK) + (col0 >> 6)) * BM + (row & 255)) * BK + (col0 & 63)) = w;
	v_add_f32_e32 v151, v164, v169
	v_mov_b32_e32 v162, v187
	v_mov_b32_e32 v163, v188
	v_mov_b32_e32 v187, v189
	v_fmamk_f32 v151, v151, 0x3a800000, v160
	v_pk_add_f32 v[162:163], v[162:163], v[186:187]
	v_rsq_f32_e32 v173, v151
	s_waitcnt lgkmcnt(0)
	v_add_f32_e32 v151, v165, v170
	v_add_f32_e32 v165, v162, v163
	v_mov_b32_e32 v162, v191
	v_mov_b32_e32 v163, v192
	v_mov_b32_e32 v191, v193
	v_pk_add_f32 v[162:163], v[162:163], v[190:191]
	ds_bpermute_b32 v167, v136, v165
	v_add_f32_e32 v162, v162, v163
	ds_bpermute_b32 v136, v136, v162
	ds_bpermute_b32 v164, v149, v151
	v_rsq_f32_e32 v153, v153
	s_waitcnt lgkmcnt(2)
	v_add_f32_e32 v163, v165, v167
	v_rsq_f32_e32 v161, v161
	s_waitcnt lgkmcnt(1)
	v_add_f32_e32 v136, v162, v136
	s_waitcnt lgkmcnt(0)
	v_add_f32_e32 v151, v151, v164
	ds_bpermute_b32 v164, v149, v163
	ds_bpermute_b32 v149, v149, v136
	v_fmamk_f32 v151, v151, 0x3a800000, v160
	v_rsq_f32_e32 v174, v151
	v_mul_f32_e32 v162, v166, v166
	s_waitcnt lgkmcnt(1)
	v_add_f32_e32 v151, v163, v164
	s_waitcnt lgkmcnt(0)
	v_add_f32_e32 v136, v136, v149
	v_fmamk_f32 v151, v151, 0x3a800000, v160
	v_fmamk_f32 v136, v136, 0x3a800000, v160
	v_rsq_f32_e32 v175, v151
	v_rsq_f32_e32 v151, v136
	v_mul_f32_e32 v136, 0xbfb8aa3b, v166
	v_pk_mul_f32 v[166:167], v[124:125], v[136:137] op_sel_hi:[1,0]
	v_pk_mul_f32 v[164:165], v[126:127], v[136:137] op_sel_hi:[1,0]
	v_pk_mul_f32 v[168:169], v[122:123], v[136:137] op_sel_hi:[1,0]
	v_pk_mul_f32 v[170:171], v[120:121], v[136:137] op_sel_hi:[1,0]
	v_exp_f32_e32 v166, v166
	v_exp_f32_e32 v167, v167
	v_exp_f32_e32 v164, v164
	v_exp_f32_e32 v165, v165
	v_exp_f32_e32 v170, v170
	v_exp_f32_e32 v168, v168
	v_exp_f32_e32 v169, v169
	v_exp_f32_e32 v171, v171
	v_pk_add_f32 v[166:167], v[166:167], 1.0 op_sel_hi:[1,0]
	v_pk_add_f32 v[164:165], v[164:165], 1.0 op_sel_hi:[1,0]
	v_pk_add_f32 v[168:169], v[168:169], 1.0 op_sel_hi:[1,0]
	v_pk_add_f32 v[170:171], v[170:171], 1.0 op_sel_hi:[1,0]
	v_rcp_f32_e32 v166, v166
	v_rcp_f32_e32 v167, v167
	v_rcp_f32_e32 v164, v164
	v_rcp_f32_e32 v165, v165
	v_rcp_f32_e32 v170, v170
	v_rcp_f32_e32 v171, v171
	v_rcp_f32_e32 v168, v168
	v_rcp_f32_e32 v169, v169
	v_pk_mul_f32 v[166:167], v[162:163], v[166:167] op_sel_hi:[0,1]
	v_pk_mul_f32 v[164:165], v[162:163], v[164:165] op_sel_hi:[0,1]
	v_pk_mul_f32 v[170:171], v[162:163], v[170:171] op_sel_hi:[0,1]
	v_pk_mul_f32 v[162:163], v[162:163], v[168:169] op_sel_hi:[0,1]
	v_pk_mul_f32 v[116:117], v[116:117], v[166:167]
	v_pk_mul_f32 v[120:121], v[114:115], v[162:163]
	v_pk_mul_f32 v[114:115], v[112:113], v[170:171]
	v_cvt_pk_bf16_f32 v112, v116, v117
	v_lshlrev_b32_e32 v116, 7, v152
	v_and_b32_e32 v136, 0x6780, v116
	v_pk_mul_f32 v[118:119], v[118:119], v[164:165]
	v_lshl_add_u64 v[116:117], s[20:21], 0, v[136:137]
	v_mov_b32_e32 v149, v137
	v_cvt_pk_bf16_f32 v113, v118, v119
	v_cvt_pk_bf16_f32 v114, v114, v115
	v_cvt_pk_bf16_f32 v115, v120, v121
	v_lshl_add_u64 v[116:117], v[116:117], 0, v[148:149]
	global_store_dwordx4 v[116:117], v[112:115], off
	s_nop 1
	v_mul_f32_e32 v112, 0xbfb8aa3b, v172
	v_pk_mul_f32 v[118:119], v[110:111], v[112:113] op_sel_hi:[1,0]
	v_pk_mul_f32 v[120:121], v[108:109], v[112:113] op_sel_hi:[1,0]
	v_pk_mul_f32 v[122:123], v[106:107], v[112:113] op_sel_hi:[1,0]
	v_pk_mul_f32 v[112:113], v[104:105], v[112:113] op_sel_hi:[1,0]
	v_exp_f32_e32 v120, v120
	v_exp_f32_e32 v121, v121
	v_exp_f32_e32 v118, v118
	v_exp_f32_e32 v119, v119
	v_exp_f32_e32 v112, v112
	v_exp_f32_e32 v122, v122
	v_exp_f32_e32 v123, v123
	v_exp_f32_e32 v113, v113
	v_pk_add_f32 v[118:119], v[118:119], 1.0 op_sel_hi:[1,0]
	v_pk_add_f32 v[120:121], v[120:121], 1.0 op_sel_hi:[1,0]
	v_pk_add_f32 v[122:123], v[122:123], 1.0 op_sel_hi:[1,0]
	v_pk_add_f32 v[112:113], v[112:113], 1.0 op_sel_hi:[1,0]
	v_rcp_f32_e32 v120, v120
	v_rcp_f32_e32 v121, v121
	v_rcp_f32_e32 v118, v118
	v_rcp_f32_e32 v119, v119
	v_rcp_f32_e32 v112, v112
	v_rcp_f32_e32 v113, v113
	v_rcp_f32_e32 v122, v122
	v_rcp_f32_e32 v123, v123
	v_mul_f32_e32 v114, v172, v172
	v_pk_mul_f32 v[120:121], v[114:115], v[120:121] op_sel_hi:[0,1]
	v_pk_mul_f32 v[118:119], v[114:115], v[118:119] op_sel_hi:[0,1]
	v_pk_mul_f32 v[112:113], v[114:115], v[112:113] op_sel_hi:[0,1]
	v_pk_mul_f32 v[114:115], v[114:115], v[122:123] op_sel_hi:[0,1]
	v_pk_mul_f32 v[102:103], v[102:103], v[118:119]
	v_pk_mul_f32 v[100:101], v[100:101], v[120:121]
	v_pk_mul_f32 v[104:105], v[98:99], v[114:115]
	v_pk_mul_f32 v[98:99], v[96:97], v[112:113]
	v_cvt_pk_bf16_f32 v96, v100, v101
	v_cvt_pk_bf16_f32 v97, v102, v103
	v_cvt_pk_bf16_f32 v98, v98, v99
	v_cvt_pk_bf16_f32 v99, v104, v105
	global_store_dwordx4 v[116:117], v[96:99], off offset:2048
	s_nop 1
	v_mul_f32_e32 v96, 0xbfb8aa3b, v153
	v_pk_mul_f32 v[102:103], v[92:93], v[96:97] op_sel_hi:[1,0]
	v_pk_mul_f32 v[100:101], v[94:95], v[96:97] op_sel_hi:[1,0]
	v_pk_mul_f32 v[104:105], v[90:91], v[96:97] op_sel_hi:[1,0]
	v_pk_mul_f32 v[96:97], v[88:89], v[96:97] op_sel_hi:[1,0]
	v_exp_f32_e32 v102, v102
	v_exp_f32_e32 v103, v103
	v_exp_f32_e32 v100, v100
	v_exp_f32_e32 v101, v101
	v_exp_f32_e32 v96, v96
	v_exp_f32_e32 v104, v104
	v_exp_f32_e32 v105, v105
	v_exp_f32_e32 v97, v97
	v_pk_add_f32 v[102:103], v[102:103], 1.0 op_sel_hi:[1,0]
	v_pk_add_f32 v[100:101], v[100:101], 1.0 op_sel_hi:[1,0]
	v_pk_add_f32 v[104:105], v[104:105], 1.0 op_sel_hi:[1,0]
	v_pk_add_f32 v[96:97], v[96:97], 1.0 op_sel_hi:[1,0]
	v_rcp_f32_e32 v102, v102
	v_rcp_f32_e32 v103, v103
	v_rcp_f32_e32 v100, v100
	v_rcp_f32_e32 v101, v101
	v_rcp_f32_e32 v96, v96
	v_rcp_f32_e32 v97, v97
	v_rcp_f32_e32 v104, v104
	v_rcp_f32_e32 v105, v105
	v_mul_f32_e32 v98, v153, v153
	v_pk_mul_f32 v[102:103], v[98:99], v[102:103] op_sel_hi:[0,1]
; __device__ __forceinline__ unsigned cvt_pk_bf16(float lo, float hi) { typedef float f2 __attribute__((ext_vector_type(2))); const bf16v2 r = __builtin_convertvector((f2){lo, hi}, bf16v2); return __builtin_bit_cast(unsigned, r); }
;     __device__ __forceinline__ void operator()(const f32x4 (&acc)[2][2][4][2], const Unit& u, int wr, int wc, int fr, int fq) const {
;     ...
;         for (int ai = 0; ai < 2; ++ai)
; #pragma unroll
;             for (int m = 0; m < 4; ++m) {
;                 const int row = row0 + ai * HALF + m * 16; const float rs = rsv[ai][m], cexp = -1.4426950408889634f * rs, rs2 = rs * rs;
;                 const f32x4 g0 = acc[ai][0][m][0], g1 = acc[ai][0][m][1], u0 = acc[ai][1][m][0], u1 = acc[ai][1][m][1];
;                 const f32x4 t0 = g0 * cexp, t1 = g1 * cexp;
;                 f32x4 d0 = (f32x4){__builtin_amdgcn_exp2f(t0[0]), __builtin_amdgcn_exp2f(t0[1]), __builtin_amdgcn_exp2f(t0[2]), __builtin_amdgcn_exp2f(t0[3])} + 1.0f;
;                 f32x4 d1 = (f32x4){__builtin_amdgcn_exp2f(t1[0]), __builtin_amdgcn_exp2f(t1[1]), __builtin_amdgcn_exp2f(t1[2]), __builtin_amdgcn_exp2f(t1[3])} + 1.0f;
;                 const f32x4 r0 = (f32x4){__builtin_amdgcn_rcpf(d0[0]), __builtin_amdgcn_rcpf(d0[1]), __builtin_amdgcn_rcpf(d0[2]), __builtin_amdgcn_rcpf(d0[3])} * rs2;
;                 const f32x4 r1 = (f32x4){__builtin_amdgcn_rcpf(d1[0]), __builtin_amdgcn_rcpf(d1[1]), __builtin_amdgcn_rcpf(d1[2]), __builtin_amdgcn_rcpf(d1[3])} * rs2;
;                 const f32x4 a0 = (g0 * u0) * r0, a1 = (g1 * u1) * r1;
;                 u32x4 w; w.x = cvt_pk_bf16(a0[0], a0[1]); w.y = cvt_pk_bf16(a0[2], a0[3]); w.z = cvt_pk_bf16(a1[0], a1[1]); w.w = cvt_pk_bf16(a1[2], a1[3]);
;                 *(u32x4*)(O + (((size_t)(row >> 8) * (DFF / BK) + (col0 >> 6)) * BM + (row & 255)) * BK + (col0 & 63)) = w;
	v_pk_mul_f32 v[100:101], v[98:99], v[100:101] op_sel_hi:[0,1]
	v_pk_mul_f32 v[96:97], v[98:99], v[96:97] op_sel_hi:[0,1]
	v_pk_mul_f32 v[98:99], v[98:99], v[104:105] op_sel_hi:[0,1]
	v_pk_mul_f32 v[84:85], v[84:85], v[102:103]
	v_pk_mul_f32 v[86:87], v[86:87], v[100:101]
	v_pk_mul_f32 v[88:89], v[82:83], v[98:99]
	v_pk_mul_f32 v[82:83], v[80:81], v[96:97]
	v_cvt_pk_bf16_f32 v80, v84, v85
	v_add_co_u32_e32 v84, vcc, s62, v116
	v_cvt_pk_bf16_f32 v81, v86, v87
	v_cvt_pk_bf16_f32 v82, v82, v83
	v_cvt_pk_bf16_f32 v83, v88, v89
	v_addc_co_u32_e32 v85, vcc, 0, v117, vcc
	global_store_dwordx4 v[84:85], v[80:83], off
	s_nop 1
	v_mul_f32_e32 v80, 0xbfb8aa3b, v161
	v_pk_mul_f32 v[86:87], v[78:79], v[80:81] op_sel_hi:[1,0]
	v_pk_mul_f32 v[88:89], v[76:77], v[80:81] op_sel_hi:[1,0]
	v_pk_mul_f32 v[90:91], v[74:75], v[80:81] op_sel_hi:[1,0]
	v_pk_mul_f32 v[80:81], v[72:73], v[80:81] op_sel_hi:[1,0]
	v_exp_f32_e32 v88, v88
	v_exp_f32_e32 v89, v89
	v_exp_f32_e32 v86, v86
	v_exp_f32_e32 v87, v87
	v_exp_f32_e32 v80, v80
	v_exp_f32_e32 v90, v90
	v_exp_f32_e32 v91, v91
	v_exp_f32_e32 v81, v81
	v_pk_add_f32 v[86:87], v[86:87], 1.0 op_sel_hi:[1,0]
	v_pk_add_f32 v[88:89], v[88:89], 1.0 op_sel_hi:[1,0]
	v_pk_add_f32 v[90:91], v[90:91], 1.0 op_sel_hi:[1,0]
	v_pk_add_f32 v[80:81], v[80:81], 1.0 op_sel_hi:[1,0]
	v_rcp_f32_e32 v88, v88
	v_rcp_f32_e32 v89, v89
	v_rcp_f32_e32 v86, v86
	v_rcp_f32_e32 v87, v87
	v_rcp_f32_e32 v80, v80
	v_rcp_f32_e32 v81, v81
	v_rcp_f32_e32 v90, v90
	v_rcp_f32_e32 v91, v91
	v_mul_f32_e32 v82, v161, v161
	v_pk_mul_f32 v[88:89], v[82:83], v[88:89] op_sel_hi:[0,1]
	v_pk_mul_f32 v[86:87], v[82:83], v[86:87] op_sel_hi:[0,1]
	v_pk_mul_f32 v[80:81], v[82:83], v[80:81] op_sel_hi:[0,1]
	v_pk_mul_f32 v[82:83], v[82:83], v[90:91] op_sel_hi:[0,1]
	v_pk_mul_f32 v[70:71], v[70:71], v[86:87]
	v_pk_mul_f32 v[68:69], v[68:69], v[88:89]
	v_pk_mul_f32 v[72:73], v[66:67], v[82:83]
	v_pk_mul_f32 v[66:67], v[64:65], v[80:81]
	v_cvt_pk_bf16_f32 v64, v68, v69
	v_cvt_pk_bf16_f32 v65, v70, v71
	v_cvt_pk_bf16_f32 v66, v66, v67
	v_cvt_pk_bf16_f32 v67, v72, v73
	global_store_dwordx4 v[84:85], v[64:67], off offset:2048
	v_mul_f32_e32 v68, v173, v173
	s_nop 0
	v_mul_f32_e32 v66, 0xbfb8aa3b, v173
	v_pk_mul_f32 v[70:71], v[62:63], v[66:67] op_sel_hi:[1,0]
	v_pk_mul_f32 v[72:73], v[60:61], v[66:67] op_sel_hi:[1,0]
	v_pk_mul_f32 v[74:75], v[58:59], v[66:67] op_sel_hi:[1,0]
	v_pk_mul_f32 v[66:67], v[56:57], v[66:67] op_sel_hi:[1,0]
	v_exp_f32_e32 v70, v70
	v_exp_f32_e32 v71, v71
	v_exp_f32_e32 v72, v72
	v_exp_f32_e32 v73, v73
	v_exp_f32_e32 v66, v66
	v_exp_f32_e32 v74, v74
	v_exp_f32_e32 v75, v75
	v_exp_f32_e32 v67, v67
	v_pk_add_f32 v[70:71], v[70:71], 1.0 op_sel_hi:[1,0]
	v_pk_add_f32 v[72:73], v[72:73], 1.0 op_sel_hi:[1,0]
	v_pk_add_f32 v[74:75], v[74:75], 1.0 op_sel_hi:[1,0]
	v_pk_add_f32 v[66:67], v[66:67], 1.0 op_sel_hi:[1,0]
	v_rcp_f32_e32 v70, v70
	v_rcp_f32_e32 v71, v71
	v_rcp_f32_e32 v72, v72
	v_rcp_f32_e32 v73, v73
	v_rcp_f32_e32 v66, v66
	v_rcp_f32_e32 v67, v67
	v_rcp_f32_e32 v74, v74
	v_rcp_f32_e32 v75, v75
	v_lshrrev_b32_e32 v64, 8, v150
	v_mad_i32_i24 v64, v64, 44, s11
	v_pk_mul_f32 v[70:71], v[68:69], v[70:71] op_sel_hi:[0,1]
	v_ashrrev_i32_e32 v65, 31, v64
	v_pk_mul_f32 v[72:73], v[68:69], v[72:73] op_sel_hi:[0,1]
	v_pk_mul_f32 v[66:67], v[68:69], v[66:67] op_sel_hi:[0,1]
	v_pk_mul_f32 v[68:69], v[68:69], v[74:75] op_sel_hi:[0,1]
	v_pk_mul_f32 v[54:55], v[54:55], v[70:71]
	v_lshlrev_b64 v[64:65], 15, v[64:65]
	v_pk_mul_f32 v[52:53], v[52:53], v[72:73]
	v_pk_mul_f32 v[56:57], v[50:51], v[68:69]
	v_pk_mul_f32 v[50:51], v[48:49], v[66:67]
	v_cvt_pk_bf16_f32 v49, v54, v55
	v_lshlrev_b32_e32 v54, 7, v150
	v_cvt_pk_bf16_f32 v48, v52, v53
	v_lshl_add_u64 v[52:53], s[36:37], 0, v[64:65]
	v_and_b32_e32 v136, 0x6780, v54
	v_lshl_add_u64 v[52:53], v[52:53], 0, v[136:137]
	v_cvt_pk_bf16_f32 v50, v50, v51
	v_cvt_pk_bf16_f32 v51, v56, v57
	v_lshl_add_u64 v[52:53], v[52:53], 0, v[148:149]
	global_store_dwordx4 v[52:53], v[48:51], off
	s_nop 1
	v_mul_f32_e32 v48, 0xbfb8aa3b, v174
	v_pk_mul_f32 v[54:55], v[46:47], v[48:49] op_sel_hi:[1,0]
	v_pk_mul_f32 v[56:57], v[44:45], v[48:49] op_sel_hi:[1,0]
	v_pk_mul_f32 v[58:59], v[42:43], v[48:49] op_sel_hi:[1,0]
	v_pk_mul_f32 v[48:49], v[40:41], v[48:49] op_sel_hi:[1,0]
	v_exp_f32_e32 v56, v56
	v_exp_f32_e32 v57, v57
	v_exp_f32_e32 v54, v54
	v_exp_f32_e32 v55, v55
; #define PG8_BAR __builtin_amdgcn_s_barrier()
;     __device__ __forceinline__ void operator()(const f32x4 (&acc)[2][2][4][2], const Unit& u, int wr, int wc, int fr, int fq) const {
;     ...
;         for (int ai = 0; ai < 2; ++ai)
; #pragma unroll
;             for (int m = 0; m < 4; ++m) {
;                 const int row = row0 + ai * HALF + m * 16; const float rs = rsv[ai][m], cexp = -1.4426950408889634f * rs, rs2 = rs * rs;
;                 const f32x4 g0 = acc[ai][0][m][0], g1 = acc[ai][0][m][1], u0 = acc[ai][1][m][0], u1 = acc[ai][1][m][1];
;                 const f32x4 t0 = g0 * cexp, t1 = g1 * cexp;
;                 f32x4 d0 = (f32x4){__builtin_amdgcn_exp2f(t0[0]), __builtin_amdgcn_exp2f(t0[1]), __builtin_amdgcn_exp2f(t0[2]), __builtin_amdgcn_exp2f(t0[3])} + 1.0f;
;                 f32x4 d1 = (f32x4){__builtin_amdgcn_exp2f(t1[0]), __builtin_amdgcn_exp2f(t1[1]), __builtin_amdgcn_exp2f(t1[2]), __builtin_amdgcn_exp2f(t1[3])} + 1.0f;
;                 const f32x4 r0 = (f32x4){__builtin_amdgcn_rcpf(d0[0]), __builtin_amdgcn_rcpf(d0[1]), __builtin_amdgcn_rcpf(d0[2]), __builtin_amdgcn_rcpf(d0[3])} * rs2;
;                 const f32x4 r1 = (f32x4){__builtin_amdgcn_rcpf(d1[0]), __builtin_amdgcn_rcpf(d1[1]), __builtin_amdgcn_rcpf(d1[2]), __builtin_amdgcn_rcpf(d1[3])} * rs2;
;                 const f32x4 a0 = (g0 * u0) * r0, a1 = (g1 * u1) * r1;
;                 u32x4 w; w.x = cvt_pk_bf16(a0[0], a0[1]); w.y = cvt_pk_bf16(a0[2], a0[3]); w.z = cvt_pk_bf16(a1[0], a1[1]); w.w = cvt_pk_bf16(a1[2], a1[3]);
;                 *(u32x4*)(O + (((size_t)(row >> 8) * (DFF / BK) + (col0 >> 6)) * BM + (row & 255)) * BK + (col0 & 63)) = w;
; template <class Epi, class Sched, bool ALIGN_EPI = false, bool SP2 = false, bool ATILED = false>
; __device__ __forceinline__ void gemm_phase(PG8_LAS unsigned char* lds, const Gemm g, const Sched& S, const Epi& E) {
;     ...
;         if constexpr (!Epi::AFTER_DRAIN) { E(acc, cur, wr, wc, fr, fq); S.done(cur); }
;         if (!has_next) break;
; #pragma unroll
;         for (int a = 0; a < 2; ++a)
; #pragma unroll
;             for (int b = 0; b < 2; ++b)
; #pragma unroll
;                 for (int m = 0; m < 4; ++m)
; #pragma unroll
;                     for (int n = 0; n < 2; ++n) acc[a][b][m][n] = (f32x4){0.f, 0.f, 0.f, 0.f};
;         cur = nxt; cA = nA; cB = nB; ++ui;
;         if constexpr (ALIGN_EPI) { if (wr == 1) PG8_BAR; }
	v_exp_f32_e32 v48, v48
	v_exp_f32_e32 v58, v58
	v_exp_f32_e32 v59, v59
	v_exp_f32_e32 v49, v49
	v_pk_add_f32 v[54:55], v[54:55], 1.0 op_sel_hi:[1,0]
	v_pk_add_f32 v[56:57], v[56:57], 1.0 op_sel_hi:[1,0]
	v_pk_add_f32 v[58:59], v[58:59], 1.0 op_sel_hi:[1,0]
	v_pk_add_f32 v[48:49], v[48:49], 1.0 op_sel_hi:[1,0]
	v_rcp_f32_e32 v56, v56
	v_rcp_f32_e32 v57, v57
	v_rcp_f32_e32 v54, v54
	v_rcp_f32_e32 v55, v55
	v_rcp_f32_e32 v48, v48
	v_rcp_f32_e32 v49, v49
	v_rcp_f32_e32 v58, v58
	v_rcp_f32_e32 v59, v59
	v_mul_f32_e32 v50, v174, v174
	v_pk_mul_f32 v[56:57], v[50:51], v[56:57] op_sel_hi:[0,1]
	v_pk_mul_f32 v[54:55], v[50:51], v[54:55] op_sel_hi:[0,1]
	v_pk_mul_f32 v[48:49], v[50:51], v[48:49] op_sel_hi:[0,1]
	v_pk_mul_f32 v[50:51], v[50:51], v[58:59] op_sel_hi:[0,1]
	v_pk_mul_f32 v[38:39], v[38:39], v[54:55]
	v_pk_mul_f32 v[36:37], v[36:37], v[56:57]
	v_pk_mul_f32 v[40:41], v[34:35], v[50:51]
	v_pk_mul_f32 v[34:35], v[32:33], v[48:49]
	v_cvt_pk_bf16_f32 v32, v36, v37
	v_cvt_pk_bf16_f32 v33, v38, v39
	v_cvt_pk_bf16_f32 v34, v34, v35
	v_cvt_pk_bf16_f32 v35, v40, v41
	global_store_dwordx4 v[52:53], v[32:35], off offset:2048
	s_nop 1
	v_mul_f32_e32 v32, 0xbfb8aa3b, v175
	v_pk_mul_f32 v[38:39], v[28:29], v[32:33] op_sel_hi:[1,0]
	v_pk_mul_f32 v[36:37], v[30:31], v[32:33] op_sel_hi:[1,0]
	v_pk_mul_f32 v[40:41], v[26:27], v[32:33] op_sel_hi:[1,0]
	v_pk_mul_f32 v[32:33], v[24:25], v[32:33] op_sel_hi:[1,0]
	v_exp_f32_e32 v38, v38
	v_exp_f32_e32 v39, v39
	v_exp_f32_e32 v36, v36
	v_exp_f32_e32 v37, v37
	v_exp_f32_e32 v32, v32
	v_exp_f32_e32 v40, v40
	v_exp_f32_e32 v41, v41
	v_exp_f32_e32 v33, v33
	v_pk_add_f32 v[38:39], v[38:39], 1.0 op_sel_hi:[1,0]
	v_pk_add_f32 v[36:37], v[36:37], 1.0 op_sel_hi:[1,0]
	v_pk_add_f32 v[40:41], v[40:41], 1.0 op_sel_hi:[1,0]
	v_pk_add_f32 v[32:33], v[32:33], 1.0 op_sel_hi:[1,0]
	v_rcp_f32_e32 v38, v38
	v_rcp_f32_e32 v39, v39
	v_rcp_f32_e32 v36, v36
	v_rcp_f32_e32 v37, v37
	v_rcp_f32_e32 v32, v32
	v_rcp_f32_e32 v33, v33
	v_rcp_f32_e32 v40, v40
	v_rcp_f32_e32 v41, v41
	v_mul_f32_e32 v34, v175, v175
	v_pk_mul_f32 v[38:39], v[34:35], v[38:39] op_sel_hi:[0,1]
	v_pk_mul_f32 v[36:37], v[34:35], v[36:37] op_sel_hi:[0,1]
	v_pk_mul_f32 v[32:33], v[34:35], v[32:33] op_sel_hi:[0,1]
	v_pk_mul_f32 v[34:35], v[34:35], v[40:41] op_sel_hi:[0,1]
	v_pk_mul_f32 v[20:21], v[20:21], v[38:39]
	v_pk_mul_f32 v[22:23], v[22:23], v[36:37]
	v_pk_mul_f32 v[24:25], v[18:19], v[34:35]
	v_pk_mul_f32 v[18:19], v[16:17], v[32:33]
	v_cvt_pk_bf16_f32 v16, v20, v21
	v_add_co_u32_e32 v20, vcc, s62, v52
	v_cvt_pk_bf16_f32 v17, v22, v23
	v_cvt_pk_bf16_f32 v18, v18, v19
	v_cvt_pk_bf16_f32 v19, v24, v25
	v_addc_co_u32_e32 v21, vcc, 0, v53, vcc
	global_store_dwordx4 v[20:21], v[16:19], off
	s_andn2_b64 vcc, exec, s[0:1]
	s_mov_b64 s[0:1], -1
	v_mul_f32_e32 v16, 0xbfb8aa3b, v151
	v_pk_mul_f32 v[22:23], v[14:15], v[16:17] op_sel_hi:[1,0]
	v_pk_mul_f32 v[24:25], v[12:13], v[16:17] op_sel_hi:[1,0]
	v_pk_mul_f32 v[26:27], v[10:11], v[16:17] op_sel_hi:[1,0]
	v_pk_mul_f32 v[16:17], v[8:9], v[16:17] op_sel_hi:[1,0]
	v_exp_f32_e32 v24, v24
	v_exp_f32_e32 v25, v25
	v_exp_f32_e32 v22, v22
	v_exp_f32_e32 v23, v23
	v_exp_f32_e32 v16, v16
	v_exp_f32_e32 v26, v26
	v_exp_f32_e32 v27, v27
	v_exp_f32_e32 v17, v17
	v_pk_add_f32 v[22:23], v[22:23], 1.0 op_sel_hi:[1,0]
	v_pk_add_f32 v[24:25], v[24:25], 1.0 op_sel_hi:[1,0]
	v_pk_add_f32 v[26:27], v[26:27], 1.0 op_sel_hi:[1,0]
	v_pk_add_f32 v[16:17], v[16:17], 1.0 op_sel_hi:[1,0]
	v_rcp_f32_e32 v24, v24
	v_rcp_f32_e32 v25, v25
	v_rcp_f32_e32 v22, v22
	v_rcp_f32_e32 v23, v23
	v_rcp_f32_e32 v16, v16
	v_rcp_f32_e32 v17, v17
	v_rcp_f32_e32 v26, v26
	v_rcp_f32_e32 v27, v27
	v_mul_f32_e32 v18, v151, v151
	v_pk_mul_f32 v[24:25], v[18:19], v[24:25] op_sel_hi:[0,1]
	v_pk_mul_f32 v[22:23], v[18:19], v[22:23] op_sel_hi:[0,1]
	v_pk_mul_f32 v[16:17], v[18:19], v[16:17] op_sel_hi:[0,1]
	v_pk_mul_f32 v[18:19], v[18:19], v[26:27] op_sel_hi:[0,1]
	v_pk_mul_f32 v[6:7], v[6:7], v[22:23]
	v_pk_mul_f32 v[4:5], v[4:5], v[24:25]
	v_pk_mul_f32 v[8:9], v[2:3], v[18:19]
	v_pk_mul_f32 v[2:3], v[0:1], v[16:17]
	v_cvt_pk_bf16_f32 v0, v4, v5
	v_cvt_pk_bf16_f32 v1, v6, v7
	v_cvt_pk_bf16_f32 v2, v2, v3
	v_cvt_pk_bf16_f32 v3, v8, v9
	global_store_dwordx4 v[20:21], v[0:3], off offset:2048
	s_cbranch_vccnz .LBB0_813
	s_andn2_b64 vcc, exec, s[4:5]
	s_cbranch_vccnz .LBB0_812
	s_barrier
	s_branch .LBB0_812
